# scan phases: state (MFMA-heavy) waves run at s_setprio 2 for the chunk loop; on top of norm-loop consolidation
# speedup vs baseline: 1.0062x; 1.0062x over previous
; template <bool GLA>
; __device__ __forceinline__ void scan_item2(LAS unsigned char* lds, const bf16* Qd, const bf16* Kd, const bf16* V, bf16* O, const float* EG, int ldqk, int ldv, int b, int h, int dvs, float e_const, int tid) {
;     ...
;         f32x4 st[16][2];
; #pragma unroll
;         for (int t = 0; t < 16; ++t) { st[t][0] = (f32x4){0.f, 0.f, 0.f, 0.f}; st[t][1] = (f32x4){0.f, 0.f, 0.f, 0.f}; }
;         bf16* const obase = O + (size_t)(b * SEQ) * ldv + h * 512 + dvs * 128 + 32 * w;
;         const unsigned ooff = (unsigned)(fr * ldv + 4 * fq) * 2u;
.LBB0_414:
	v_cvt_f32_ubyte0_e32 v2, s9
	v_sub_f32_e32 v2, 0xc0a00000, v2
	v_cmp_gt_f32_e32 vcc, s42, v2
	s_and_b64 s[6:7], vcc, exec
	s_cselect_b32 s0, 0xffffffc0, 0
	v_cndmask_b32_e32 v3, 0, v250, vcc
	v_add_f32_e32 v2, v2, v3
	v_exp_f32_e32 v2, v2
	s_nop 0
	v_ldexp_f32 v18, v2, s0
	v_sub_f32_e32 v4, 1.0, v18
	v_cvt_f64_f32_e32 v[2:3], v4
	v_frexp_exp_i32_f64_e32 v2, v[2:3]
	v_frexp_mant_f32_e32 v3, v4
	s_mov_b32 s0, 0x3f2aaaab
	v_cmp_gt_f32_e32 vcc, s0, v3
	v_add_f32_e32 v6, -1.0, v4
	v_sub_f32_e64 v7, -v18, v6
	v_subbrev_co_u32_e32 v3, vcc, 0, v2, vcc
	v_cvt_f32_i32_e32 v2, v3
	v_sub_u32_e32 v3, 0, v3
	v_ldexp_f32 v5, v4, v3
	v_sub_f32_e32 v4, v6, v4
	v_add_f32_e32 v4, 1.0, v4
	v_add_f32_e32 v9, -1.0, v5
	v_add_f32_e32 v4, v7, v4
	v_ldexp_f32 v3, v4, v3
	v_add_f32_e32 v4, 1.0, v9
	v_sub_f32_e32 v4, v5, v4
	v_add_f32_e32 v10, v3, v4
	v_add_f32_e32 v4, 1.0, v5
	v_add_f32_e32 v6, -1.0, v4
	v_sub_f32_e32 v5, v5, v6
	v_add_f32_e32 v3, v3, v5
	v_add_f32_e32 v12, v4, v3
	v_rcp_f32_e32 v13, v12
	v_add_f32_e32 v5, v9, v10
	v_sub_f32_e32 v4, v12, v4
	v_sub_f32_e32 v3, v3, v4
	v_mul_f32_e32 v14, v5, v13
	v_mul_f32_e32 v6, v12, v14
	v_fma_f32 v8, v14, v12, -v6
	v_fmac_f32_e32 v8, v14, v3
	v_add_f32_e32 v4, v6, v8
	v_sub_f32_e32 v7, v5, v4
	v_sub_f32_e32 v9, v5, v9
	v_sub_f32_e32 v15, v10, v9
	v_pk_add_f32 v[10:11], v[4:5], v[6:7] neg_lo:[0,1] neg_hi:[0,1]
	v_mov_b32_e32 v9, v4
	v_pk_add_f32 v[4:5], v[10:11], v[8:9] neg_lo:[0,1] neg_hi:[0,1]
	s_mov_b32 s0, 0x3f317218
	v_add_f32_e32 v5, v15, v5
	v_add_f32_e32 v10, v4, v5
	v_add_f32_e32 v5, v7, v10
	v_mul_f32_e32 v4, v13, v5
	v_add_f32_e32 v15, v14, v4
	v_sub_f32_e32 v6, v15, v14
	v_mul_f32_e32 v8, v12, v4
	v_sub_f32_e32 v14, v4, v6
	v_fma_f32 v6, v4, v12, -v8
	v_fmac_f32_e32 v6, v4, v3
	v_add_f32_e32 v4, v8, v6
	v_sub_f32_e32 v9, v5, v4
	v_sub_f32_e32 v3, v7, v5
	v_add_f32_e32 v3, v10, v3
	v_pk_add_f32 v[10:11], v[4:5], v[8:9] neg_lo:[0,1] neg_hi:[0,1]
	v_mov_b32_e32 v7, v4
	v_pk_add_f32 v[4:5], v[10:11], v[6:7] neg_lo:[0,1] neg_hi:[0,1]
	v_mov_b32_e32 v8, 0x3ecc95a3
	v_add_f32_e32 v3, v3, v5
	v_add_f32_e32 v3, v4, v3
	v_add_f32_e32 v3, v9, v3
	v_mul_f32_e32 v3, v13, v3
	v_add_f32_e32 v4, v14, v3
	v_add_f32_e32 v6, v15, v4
	v_mul_f32_e32 v7, v6, v6
	v_fmamk_f32 v8, v7, 0x3e9b6dac, v8
	v_ldexp_f32 v5, v6, 1
	v_mul_f32_e32 v3, v6, v7
	v_fmaak_f32 v217, v7, v8, 0x3f2aaada
	v_sub_f32_e32 v6, v6, v15
	v_sub_f32_e32 v4, v4, v6
	v_pk_mul_f32 v[6:7], v[2:3], v[216:217]
	v_ldexp_f32 v8, v4, 1
	v_fma_f32 v4, v2, s0, -v6
	v_fmac_f32_e32 v4, 0xb102e308, v2
	v_pk_add_f32 v[2:3], v[6:7], v[4:5]
	v_cmp_nlt_f32_e32 vcc, 1.0, v18
	v_sub_f32_e32 v5, v3, v5
	v_sub_f32_e32 v5, v7, v5
	v_add_f32_e32 v9, v8, v5
	v_mov_b32_e32 v8, v6
	v_pk_add_f32 v[6:7], v[2:3], v[6:7] neg_lo:[0,1] neg_hi:[0,1]
	v_pk_add_f32 v[10:11], v[2:3], v[8:9]
	v_mov_b32_e32 v5, v2
	v_mov_b32_e32 v7, v11
	v_pk_add_f32 v[12:13], v[4:5], v[6:7] neg_lo:[0,1] neg_hi:[0,1]
	v_pk_add_f32 v[4:5], v[4:5], v[6:7]
	v_mov_b32_e32 v16, v3
	v_pk_add_f32 v[6:7], v[4:5], v[2:3] op_sel:[1,0] op_sel_hi:[0,1] neg_lo:[0,1] neg_hi:[0,1]
	v_pk_add_f32 v[14:15], v[10:11], v[6:7] op_sel_hi:[1,0] neg_lo:[0,1] neg_hi:[0,1]
	v_mov_b32_e32 v10, v11
	v_mov_b32_e32 v11, v5
	v_mov_b32_e32 v17, v6
	v_pk_add_f32 v[6:7], v[10:11], v[16:17] neg_lo:[0,1] neg_hi:[0,1]
	v_mov_b32_e32 v8, v9
	v_mov_b32_e32 v9, v2
	v_pk_add_f32 v[2:3], v[8:9], v[6:7] neg_lo:[0,1] neg_hi:[0,1]
	v_mov_b32_e32 v14, v12
	v_pk_add_f32 v[6:7], v[14:15], v[2:3]
	v_mov_b32_e32 v13, v5
	v_pk_add_f32 v[8:9], v[6:7], v[6:7] op_sel:[0,1] op_sel_hi:[1,0]
	s_mov_b32 s0, 0x33800000
	v_pk_add_f32 v[4:5], v[4:5], v[8:9] op_sel:[1,0] op_sel_hi:[0,1]
	v_mov_b32_e32 v7, v4
	v_pk_add_f32 v[10:11], v[6:7], v[12:13] neg_lo:[0,1] neg_hi:[0,1]
	v_mov_b32_e32 v3, v8
	v_sub_f32_e32 v5, v6, v10
	v_pk_add_f32 v[2:3], v[2:3], v[10:11] neg_lo:[0,1] neg_hi:[0,1]
	v_sub_f32_e32 v5, v12, v5
	v_add_f32_e32 v2, v2, v5
	v_add_f32_e32 v2, v2, v3
	v_add_f32_e32 v2, v4, v2
	v_cndmask_b32_e32 v2, v251, v2, vcc
	v_cmp_neq_f32_e32 vcc, 1.0, v18
	s_nop 1
	v_cndmask_b32_e32 v2, v252, v2, vcc
	v_cmp_gt_f32_e32 vcc, s0, v18
	s_nop 1
	v_cndmask_b32_e64 v2, v2, -v18, vcc
	v_mul_f32_e32 v2, 0x3fb8aa3b, v2
	v_mul_f32_e32 v3, 0x42800000, v2
	v_cmp_gt_f32_e32 vcc, s42, v3
	s_and_b64 s[6:7], vcc, exec
	s_cselect_b32 s0, 0xffffffc0, 0
	v_cndmask_b32_e32 v3, 0, v250, vcc
	v_fmac_f32_e32 v3, 0x42800000, v2
	v_exp_f32_e32 v3, v3
	s_lshl_b32 s6, s10, 11
	s_ashr_i32 s7, s6, 31
	s_lshl_b64 s[6:7], s[6:7], 13
	v_ldexp_f32 v218, v3, s0
	s_lshl_b32 s12, s8, 5
	s_and_b32 s0, s84, 0x1c00
	s_ashr_i32 s13, s12, 31
	s_or_b32 s6, s6, s0
	s_andn2_b32 s11, s11, 63
	s_or_b64 s[6:7], s[6:7], s[60:61]
	s_lshl_b64 s[12:13], s[12:13], 1
	s_add_u32 s6, s6, s12
	v_mov_b32_e32 v2, 0
	v_or_b32_e32 v3, s11, v224
	s_addc_u32 s7, s7, s13
	v_mov_b32_e32 v220, v218
	v_mov_b32_e32 v221, v218
	v_lshl_add_u64 v[222:223], v[212:213], 0, s[6:7]
	s_mov_b64 s[6:7], 0
	v_add_u32_e32 v215, v226, v3
	v_mov_b32_e32 v3, v2
	v_mov_b32_e32 v4, v2
	v_mov_b32_e32 v5, v2
	v_mov_b32_e32 v30, v2
	v_mov_b32_e32 v31, v2
	v_mov_b32_e32 v32, v2
	v_mov_b32_e32 v33, v2
	v_mov_b32_e32 v34, v2
	v_mov_b32_e32 v35, v2
	v_mov_b32_e32 v36, v2
	v_mov_b32_e32 v37, v2
	v_mov_b32_e32 v38, v2
	v_mov_b32_e32 v39, v2
	v_mov_b32_e32 v40, v2
	v_mov_b32_e32 v41, v2
	v_mov_b32_e32 v58, v2
	v_mov_b32_e32 v59, v2
	v_mov_b32_e32 v60, v2
	v_mov_b32_e32 v61, v2
	v_mov_b32_e32 v62, v2
	v_mov_b32_e32 v63, v2
	v_mov_b32_e32 v64, v2
	v_mov_b32_e32 v65, v2
	v_mov_b32_e32 v6, v2
	v_mov_b32_e32 v7, v2
	v_mov_b32_e32 v8, v2
	v_mov_b32_e32 v9, v2
	v_mov_b32_e32 v10, v2
	v_mov_b32_e32 v11, v2
	v_mov_b32_e32 v12, v2
	v_mov_b32_e32 v13, v2
; __device__ __forceinline__ unsigned cvt2(float a, float b) { f32x2s v = {a, b}; bf16x2_t r = __builtin_convertvector(v, bf16x2_t); return __builtin_bit_cast(unsigned, r); }
; #define SC_BAR() do { asm volatile("s_waitcnt lgkmcnt(0)" ::: "memory"); __builtin_amdgcn_s_barrier(); asm volatile("" ::: "memory"); } while (0)
; template <bool GLA>
; __device__ __forceinline__ void scan_item2(LAS unsigned char* lds, const bf16* Qd, const bf16* Kd, const bf16* V, bf16* O, const float* EG, int ldqk, int ldv, int b, int h, int dvs, float e_const, int tid) {
;     ...
;         for (int t = 0; t < 16; ++t) { st[t][0] = (f32x4){0.f, 0.f, 0.f, 0.f}; st[t][1] = (f32x4){0.f, 0.f, 0.f, 0.f}; }
;         bf16* const obase = O + (size_t)(b * SEQ) * ldv + h * 512 + dvs * 128 + 32 * w;
;         const unsigned ooff = (unsigned)(fr * ldv + 4 * fq) * 2u;
;         for (int c = 0; c < SEQ / 64; ++c) {
;             SC_BAR();
;             f32x4 oa[4][2];
; #pragma unroll
;             for (int ti = 0; ti < 4; ++ti) { oa[ti][0] = (f32x4){0.f, 0.f, 0.f, 0.f}; oa[ti][1] = (f32x4){0.f, 0.f, 0.f, 0.f}; }
;             v2u faq[2][4][2];
;     ...
;             s16x4 fkt[3][2][2]; bf16x8s bv[2][2];
;     ...
;             LD_C1(0, 0);
; #pragma unroll
;             for (int s_ = 0; s_ < 8; ++s_) {
;                 if (s_ + 1 < 8) LD_C1((s_ + 1) & 1, s_ + 1); else { LD_C2(0, 0); LD_C2(1, 1); }
;                 __builtin_amdgcn_sched_barrier(0);
; #pragma unroll
;                 for (int ct = 0; ct < 2; ++ct) {
;                     v4u sbw; sbw.x = cvt2(st[2 * s_][ct][0], st[2 * s_][ct][1]); sbw.y = cvt2(st[2 * s_][ct][2], st[2 * s_][ct][3]); sbw.z = cvt2(st[2 * s_ + 1][ct][0], st[2 * s_ + 1][ct][1]); sbw.w = cvt2(st[2 * s_ + 1][ct][2], st[2 * s_ + 1][ct][3]);
;                     const bf16x8s sb = __builtin_bit_cast(bf16x8s, sbw);
; #pragma unroll
;                     for (int ti = 0; ti < 4; ++ti) { v4u aw; aw.x = faq[s_ & 1][ti][0].x; aw.y = faq[s_ & 1][ti][0].y; aw.z = faq[s_ & 1][ti][1].x; aw.w = faq[s_ & 1][ti][1].y;
;                         oa[ti][ct] = __builtin_amdgcn_mfma_f32_16x16x32_bf16(sb, __builtin_bit_cast(bf16x8s, aw), oa[ti][ct], 0, 0, 0); } }
	v_mov_b32_e32 v14, v2
	v_mov_b32_e32 v15, v2
	v_mov_b32_e32 v16, v2
	v_mov_b32_e32 v17, v2
	v_mov_b32_e32 v18, v2
	v_mov_b32_e32 v19, v2
	v_mov_b32_e32 v20, v2
	v_mov_b32_e32 v21, v2
	v_mov_b32_e32 v22, v2
	v_mov_b32_e32 v23, v2
	v_mov_b32_e32 v24, v2
	v_mov_b32_e32 v25, v2
	v_mov_b32_e32 v26, v2
	v_mov_b32_e32 v27, v2
	v_mov_b32_e32 v28, v2
	v_mov_b32_e32 v29, v2
	v_mov_b32_e32 v42, v2
	v_mov_b32_e32 v43, v2
	v_mov_b32_e32 v44, v2
	v_mov_b32_e32 v45, v2
	v_mov_b32_e32 v46, v2
	v_mov_b32_e32 v47, v2
	v_mov_b32_e32 v48, v2
	v_mov_b32_e32 v49, v2
	v_mov_b32_e32 v50, v2
	v_mov_b32_e32 v51, v2
	v_mov_b32_e32 v52, v2
	v_mov_b32_e32 v53, v2
	v_mov_b32_e32 v54, v2
	v_mov_b32_e32 v55, v2
	v_mov_b32_e32 v56, v2
	v_mov_b32_e32 v57, v2
	v_mov_b32_e32 v66, v2
	v_mov_b32_e32 v67, v2
	v_mov_b32_e32 v68, v2
	v_mov_b32_e32 v69, v2
	v_mov_b32_e32 v70, v2
	v_mov_b32_e32 v71, v2
	v_mov_b32_e32 v72, v2
	v_mov_b32_e32 v73, v2
	v_mov_b32_e32 v74, v2
	v_mov_b32_e32 v75, v2
	v_mov_b32_e32 v76, v2
	v_mov_b32_e32 v77, v2
	v_mov_b32_e32 v78, v2
	v_mov_b32_e32 v79, v2
	v_mov_b32_e32 v80, v2
	v_mov_b32_e32 v81, v2
	v_mov_b32_e32 v82, v2
	v_mov_b32_e32 v83, v2
	v_mov_b32_e32 v84, v2
	v_mov_b32_e32 v85, v2
	v_mov_b32_e32 v86, v2
	v_mov_b32_e32 v87, v2
	v_mov_b32_e32 v88, v2
	v_mov_b32_e32 v89, v2
	v_mov_b32_e32 v90, v2
	v_mov_b32_e32 v91, v2
	v_mov_b32_e32 v92, v2
	v_mov_b32_e32 v93, v2
	v_mov_b32_e32 v94, v2
	v_mov_b32_e32 v95, v2
	v_mov_b32_e32 v96, v2
	v_mov_b32_e32 v97, v2
	v_mov_b32_e32 v98, v2
	v_mov_b32_e32 v99, v2
	v_mov_b32_e32 v100, v2
	v_mov_b32_e32 v101, v2
	v_mov_b32_e32 v102, v2
	v_mov_b32_e32 v103, v2
	v_mov_b32_e32 v104, v2
	v_mov_b32_e32 v105, v2
	v_mov_b32_e32 v106, v2
	v_mov_b32_e32 v107, v2
	v_mov_b32_e32 v108, v2
	v_mov_b32_e32 v109, v2
	v_mov_b32_e32 v110, v2
	v_mov_b32_e32 v111, v2
	v_mov_b32_e32 v112, v2
	v_mov_b32_e32 v113, v2
	v_mov_b32_e32 v114, v2
	v_mov_b32_e32 v115, v2
	v_mov_b32_e32 v116, v2
	v_mov_b32_e32 v117, v2
	v_mov_b32_e32 v118, v2
	v_mov_b32_e32 v119, v2
	v_mov_b32_e32 v120, v2
	v_mov_b32_e32 v121, v2
	v_mov_b32_e32 v122, v2
	v_mov_b32_e32 v123, v2
	v_mov_b32_e32 v124, v2
	v_mov_b32_e32 v125, v2
	v_mov_b32_e32 v126, v2
	v_mov_b32_e32 v127, v2
	v_mov_b32_e32 v128, v2
	v_mov_b32_e32 v129, v2
	s_setprio 2
.LBB0_415:
	s_waitcnt lgkmcnt(0)
	s_barrier
	v_add_u32_e32 v198, 0x2000, v248
	v_add_u32_e32 v202, 0x4000, v248
	v_add_u32_e32 v217, 0x6000, v248
	ds_read2_b64 v[130:133], v248 offset1:4
	ds_read2_b64 v[134:137], v198 offset0:32 offset1:36
	ds_read2_b64 v[138:141], v202 offset0:64 offset1:68
	ds_read2_b64 v[142:145], v217 offset0:96 offset1:100
	ds_read2_b64 v[146:149], v248 offset0:8 offset1:12
	ds_read2_b64 v[150:153], v198 offset0:40 offset1:44
	ds_read2_b64 v[154:157], v202 offset0:72 offset1:76
	ds_read2_b64 v[158:161], v217 offset0:104 offset1:108
	v_cvt_pk_bf16_f32 v162, v126, v127
	v_cvt_pk_bf16_f32 v163, v128, v129
	v_cvt_pk_bf16_f32 v164, v118, v119
	v_cvt_pk_bf16_f32 v165, v120, v121
	v_cvt_pk_bf16_f32 v178, v122, v123
	v_cvt_pk_bf16_f32 v179, v124, v125
	v_cvt_pk_bf16_f32 v180, v114, v115
	v_cvt_pk_bf16_f32 v181, v116, v117
	s_waitcnt lgkmcnt(0)
	v_mfma_f32_16x16x32_bf16 v[166:169], v[162:165], v[130:133], 0
	v_mfma_f32_16x16x32_bf16 v[170:173], v[162:165], v[134:137], 0
	v_mfma_f32_16x16x32_bf16 v[174:177], v[162:165], v[138:141], 0
	v_mfma_f32_16x16x32_bf16 v[162:165], v[162:165], v[142:145], 0
	v_mfma_f32_16x16x32_bf16 v[130:133], v[178:181], v[130:133], 0
	v_mfma_f32_16x16x32_bf16 v[134:137], v[178:181], v[134:137], 0
	v_mfma_f32_16x16x32_bf16 v[138:141], v[178:181], v[138:141], 0
	v_mfma_f32_16x16x32_bf16 v[142:145], v[178:181], v[142:145], 0
	ds_read2_b64 v[178:181], v248 offset0:16 offset1:20
	ds_read2_b64 v[182:185], v198 offset0:48 offset1:52
	ds_read2_b64 v[186:189], v202 offset0:80 offset1:84
	ds_read2_b64 v[190:193], v217 offset0:112 offset1:116
	v_cvt_pk_bf16_f32 v194, v110, v111
	v_cvt_pk_bf16_f32 v195, v112, v113
	v_cvt_pk_bf16_f32 v196, v102, v103
	v_cvt_pk_bf16_f32 v197, v104, v105
	s_nop 1
	v_mfma_f32_16x16x32_bf16 v[166:169], v[194:197], v[146:149], v[166:169]
	v_mfma_f32_16x16x32_bf16 v[170:173], v[194:197], v[150:153], v[170:173]
	v_mfma_f32_16x16x32_bf16 v[174:177], v[194:197], v[154:157], v[174:177]
	v_mfma_f32_16x16x32_bf16 v[162:165], v[194:197], v[158:161], v[162:165]
	v_cvt_pk_bf16_f32 v194, v106, v107
	v_cvt_pk_bf16_f32 v195, v108, v109
	v_cvt_pk_bf16_f32 v196, v98, v99
	v_cvt_pk_bf16_f32 v197, v100, v101
	s_nop 1
	v_mfma_f32_16x16x32_bf16 v[130:133], v[194:197], v[146:149], v[130:133]
	v_mfma_f32_16x16x32_bf16 v[134:137], v[194:197], v[150:153], v[134:137]
	v_mfma_f32_16x16x32_bf16 v[138:141], v[194:197], v[154:157], v[138:141]
	v_mfma_f32_16x16x32_bf16 v[142:145], v[194:197], v[158:161], v[142:145]
	ds_read2_b64 v[146:149], v248 offset0:24 offset1:28
	ds_read2_b64 v[150:153], v198 offset0:56 offset1:60
	ds_read2_b64 v[154:157], v202 offset0:88 offset1:92
	ds_read2_b64 v[158:161], v217 offset0:120 offset1:124
	v_cvt_pk_bf16_f32 v194, v94, v95
	v_cvt_pk_bf16_f32 v195, v96, v97
	v_cvt_pk_bf16_f32 v196, v86, v87
	v_cvt_pk_bf16_f32 v197, v88, v89
	s_waitcnt lgkmcnt(0)
; __device__ __forceinline__ unsigned cvt2(float a, float b) { f32x2s v = {a, b}; bf16x2_t r = __builtin_convertvector(v, bf16x2_t); return __builtin_bit_cast(unsigned, r); }
; #define LD_C1(buf, s_) do { _Pragma("unroll") for (int ti = 0; ti < 4; ++ti) { LAS const unsigned char* ap_ = lds + SC_QI + (16 * ti + fr) * SC_QS + (32 * (s_) + 4 * fq) * 2; \
;                 faq[buf][ti][0] = *(const LAS v2u*)ap_; faq[buf][ti][1] = *(const LAS v2u*)(ap_ + 32); } } while (0)
; #define LD_C2(buf, g) do { const int ks_ = (g) >> 3, t0_ = 2 * ((g) & 7); _Pragma("unroll") for (int t = 0; t < 2; ++t) { \
;                 fkt[buf][t][0] = ldtr(lds + SC_KI + (32 * ks_ + 8 * fq + q4) * SC_KS + (16 * (t0_ + t) + 4 * p4) * 2); \
;                 fkt[buf][t][1] = ldtr(lds + SC_KI + (32 * ks_ + 8 * fq + 4 + q4) * SC_KS + (16 * (t0_ + t) + 4 * p4) * 2); } } while (0)
; template <bool GLA>
; __device__ __forceinline__ void scan_item2(LAS unsigned char* lds, const bf16* Qd, const bf16* Kd, const bf16* V, bf16* O, const float* EG, int ldqk, int ldv, int b, int h, int dvs, float e_const, int tid) {
;     ...
;             for (int s_ = 0; s_ < 8; ++s_) {
;                 if (s_ + 1 < 8) LD_C1((s_ + 1) & 1, s_ + 1); else { LD_C2(0, 0); LD_C2(1, 1); }
;                 __builtin_amdgcn_sched_barrier(0);
; #pragma unroll
;                 for (int ct = 0; ct < 2; ++ct) {
;                     v4u sbw; sbw.x = cvt2(st[2 * s_][ct][0], st[2 * s_][ct][1]); sbw.y = cvt2(st[2 * s_][ct][2], st[2 * s_][ct][3]); sbw.z = cvt2(st[2 * s_ + 1][ct][0], st[2 * s_ + 1][ct][1]); sbw.w = cvt2(st[2 * s_ + 1][ct][2], st[2 * s_ + 1][ct][3]);
;                     const bf16x8s sb = __builtin_bit_cast(bf16x8s, sbw);
; #pragma unroll
;                     for (int ti = 0; ti < 4; ++ti) { v4u aw; aw.x = faq[s_ & 1][ti][0].x; aw.y = faq[s_ & 1][ti][0].y; aw.z = faq[s_ & 1][ti][1].x; aw.w = faq[s_ & 1][ti][1].y;
;                         oa[ti][ct] = __builtin_amdgcn_mfma_f32_16x16x32_bf16(sb, __builtin_bit_cast(bf16x8s, aw), oa[ti][ct], 0, 0, 0); } }
	s_nop 0
	v_mfma_f32_16x16x32_bf16 v[166:169], v[194:197], v[178:181], v[166:169]
	v_mfma_f32_16x16x32_bf16 v[170:173], v[194:197], v[182:185], v[170:173]
	v_mfma_f32_16x16x32_bf16 v[174:177], v[194:197], v[186:189], v[174:177]
	v_mfma_f32_16x16x32_bf16 v[162:165], v[194:197], v[190:193], v[162:165]
	v_cvt_pk_bf16_f32 v194, v90, v91
	v_cvt_pk_bf16_f32 v195, v92, v93
	v_cvt_pk_bf16_f32 v196, v82, v83
	v_cvt_pk_bf16_f32 v197, v84, v85
	s_nop 1
	v_mfma_f32_16x16x32_bf16 v[130:133], v[194:197], v[178:181], v[130:133]
	v_mfma_f32_16x16x32_bf16 v[134:137], v[194:197], v[182:185], v[134:137]
	v_mfma_f32_16x16x32_bf16 v[138:141], v[194:197], v[186:189], v[138:141]
	v_mfma_f32_16x16x32_bf16 v[142:145], v[194:197], v[190:193], v[142:145]
	ds_read2_b64 v[178:181], v248 offset0:32 offset1:36
	ds_read2_b64 v[182:185], v198 offset0:64 offset1:68
	ds_read2_b64 v[186:189], v202 offset0:96 offset1:100
	ds_read2_b64 v[190:193], v217 offset0:128 offset1:132
	v_cvt_pk_bf16_f32 v194, v78, v79
	v_cvt_pk_bf16_f32 v195, v80, v81
	v_cvt_pk_bf16_f32 v196, v70, v71
	v_cvt_pk_bf16_f32 v197, v72, v73
	s_nop 1
	v_mfma_f32_16x16x32_bf16 v[166:169], v[194:197], v[146:149], v[166:169]
	v_mfma_f32_16x16x32_bf16 v[170:173], v[194:197], v[150:153], v[170:173]
	v_mfma_f32_16x16x32_bf16 v[174:177], v[194:197], v[154:157], v[174:177]
	v_mfma_f32_16x16x32_bf16 v[162:165], v[194:197], v[158:161], v[162:165]
	v_cvt_pk_bf16_f32 v194, v74, v75
	v_cvt_pk_bf16_f32 v195, v76, v77
	v_cvt_pk_bf16_f32 v196, v66, v67
	v_cvt_pk_bf16_f32 v197, v68, v69
	s_nop 1
	v_mfma_f32_16x16x32_bf16 v[130:133], v[194:197], v[146:149], v[130:133]
	v_mfma_f32_16x16x32_bf16 v[134:137], v[194:197], v[150:153], v[134:137]
	v_mfma_f32_16x16x32_bf16 v[138:141], v[194:197], v[154:157], v[138:141]
	v_mfma_f32_16x16x32_bf16 v[142:145], v[194:197], v[158:161], v[142:145]
	ds_read2_b64 v[146:149], v248 offset0:40 offset1:44
	ds_read2_b64 v[150:153], v198 offset0:72 offset1:76
	ds_read2_b64 v[154:157], v202 offset0:104 offset1:108
	ds_read2_b64 v[158:161], v217 offset0:136 offset1:140
	v_cvt_pk_bf16_f32 v194, v54, v55
	v_cvt_pk_bf16_f32 v195, v56, v57
	v_cvt_pk_bf16_f32 v196, v46, v47
	v_cvt_pk_bf16_f32 v197, v48, v49
	s_waitcnt lgkmcnt(0)
	s_nop 0
	v_mfma_f32_16x16x32_bf16 v[166:169], v[194:197], v[178:181], v[166:169]
	v_mfma_f32_16x16x32_bf16 v[170:173], v[194:197], v[182:185], v[170:173]
	v_mfma_f32_16x16x32_bf16 v[174:177], v[194:197], v[186:189], v[174:177]
	v_mfma_f32_16x16x32_bf16 v[162:165], v[194:197], v[190:193], v[162:165]
	v_cvt_pk_bf16_f32 v194, v50, v51
	v_cvt_pk_bf16_f32 v195, v52, v53
	v_cvt_pk_bf16_f32 v196, v42, v43
	v_cvt_pk_bf16_f32 v197, v44, v45
	s_nop 1
	v_mfma_f32_16x16x32_bf16 v[130:133], v[194:197], v[178:181], v[130:133]
	v_mfma_f32_16x16x32_bf16 v[134:137], v[194:197], v[182:185], v[134:137]
	v_mfma_f32_16x16x32_bf16 v[138:141], v[194:197], v[186:189], v[138:141]
	v_mfma_f32_16x16x32_bf16 v[142:145], v[194:197], v[190:193], v[142:145]
	ds_read2_b64 v[178:181], v248 offset0:48 offset1:52
	ds_read2_b64 v[182:185], v198 offset0:80 offset1:84
	ds_read2_b64 v[186:189], v202 offset0:112 offset1:116
	ds_read2_b64 v[190:193], v217 offset0:144 offset1:148
	v_cvt_pk_bf16_f32 v194, v26, v27
	v_cvt_pk_bf16_f32 v195, v28, v29
	v_cvt_pk_bf16_f32 v196, v18, v19
	v_cvt_pk_bf16_f32 v197, v20, v21
	s_nop 1
	v_mfma_f32_16x16x32_bf16 v[166:169], v[194:197], v[146:149], v[166:169]
	v_mfma_f32_16x16x32_bf16 v[170:173], v[194:197], v[150:153], v[170:173]
	v_mfma_f32_16x16x32_bf16 v[174:177], v[194:197], v[154:157], v[174:177]
	v_mfma_f32_16x16x32_bf16 v[162:165], v[194:197], v[158:161], v[162:165]
	v_cvt_pk_bf16_f32 v194, v22, v23
	v_cvt_pk_bf16_f32 v195, v24, v25
	v_cvt_pk_bf16_f32 v196, v14, v15
	v_cvt_pk_bf16_f32 v197, v16, v17
	s_nop 1
	v_mfma_f32_16x16x32_bf16 v[130:133], v[194:197], v[146:149], v[130:133]
	v_mfma_f32_16x16x32_bf16 v[134:137], v[194:197], v[150:153], v[134:137]
	v_mfma_f32_16x16x32_bf16 v[138:141], v[194:197], v[154:157], v[138:141]
	v_mfma_f32_16x16x32_bf16 v[142:145], v[194:197], v[158:161], v[142:145]
	ds_read2_b64 v[194:197], v248 offset0:56 offset1:60
	ds_read2_b64 v[198:201], v198 offset0:88 offset1:92
	ds_read2_b64 v[202:205], v202 offset0:120 offset1:124
	ds_read2_b64 v[244:247], v217 offset0:152 offset1:156
	v_cvt_pk_bf16_f32 v146, v10, v11
	v_cvt_pk_bf16_f32 v147, v12, v13
	v_cvt_pk_bf16_f32 v148, v62, v63
	v_cvt_pk_bf16_f32 v149, v64, v65
	v_cvt_pk_bf16_f32 v158, v6, v7
	v_cvt_pk_bf16_f32 v159, v8, v9
	v_cvt_pk_bf16_f32 v160, v58, v59
	v_cvt_pk_bf16_f32 v161, v60, v61
	s_waitcnt lgkmcnt(0)
	v_mfma_f32_16x16x32_bf16 v[150:153], v[146:149], v[178:181], v[166:169]
	v_mfma_f32_16x16x32_bf16 v[154:157], v[146:149], v[182:185], v[170:173]
	v_mfma_f32_16x16x32_bf16 v[166:169], v[146:149], v[186:189], v[174:177]
	v_mfma_f32_16x16x32_bf16 v[146:149], v[146:149], v[190:193], v[162:165]
	v_mfma_f32_16x16x32_bf16 v[130:133], v[158:161], v[178:181], v[130:133]
	v_mfma_f32_16x16x32_bf16 v[134:137], v[158:161], v[182:185], v[134:137]
	v_mfma_f32_16x16x32_bf16 v[138:141], v[158:161], v[186:189], v[138:141]
	v_mfma_f32_16x16x32_bf16 v[142:145], v[158:161], v[190:193], v[142:145]
	s_waitcnt vmcnt(0)
; __device__ __forceinline__ s16x4 ldtr(LAS const unsigned char* p) { return __builtin_bit_cast(s16x4, __builtin_amdgcn_ds_read_tr16_b64_v4i16((LAS s16x4*)p)); }
; #define LD_C2(buf, g) do { const int ks_ = (g) >> 3, t0_ = 2 * ((g) & 7); _Pragma("unroll") for (int t = 0; t < 2; ++t) { \
;                 fkt[buf][t][0] = ldtr(lds + SC_KI + (32 * ks_ + 8 * fq + q4) * SC_KS + (16 * (t0_ + t) + 4 * p4) * 2); \
;                 fkt[buf][t][1] = ldtr(lds + SC_KI + (32 * ks_ + 8 * fq + 4 + q4) * SC_KS + (16 * (t0_ + t) + 4 * p4) * 2); } } while (0)
; template <bool GLA>
; __device__ __forceinline__ void scan_item2(LAS unsigned char* lds, const bf16* Qd, const bf16* Kd, const bf16* V, bf16* O, const float* EG, int ldqk, int ldv, int b, int h, int dvs, float e_const, int tid) {
;     ...
; #pragma unroll
;             for (int ks = 0; ks < 2; ++ks)
; #pragma unroll
;                 for (int ct = 0; ct < 2; ++ct) { const s16x4 lo = ldtr(lds + SC_VI + (32 * ks + 8 * fq + q4) * SC_VS + (32 * w + 16 * ct + 4 * p4) * 2), hi = ldtr(lds + SC_VI + (32 * ks + 8 * fq + 4 + q4) * SC_VS + (32 * w + 16 * ct + 4 * p4) * 2);
;                     bv[ks][ct] = __builtin_shufflevector(lo, hi, 0, 1, 2, 3, 4, 5, 6, 7); }
; #pragma unroll
;             for (int g = 0; g < 16; ++g) {
;                 if (g + 2 < 16) LD_C2((g + 2) % 3, g + 2);
;                 __builtin_amdgcn_sched_barrier(0);
; #pragma unroll
;                 for (int t = 0; t < 2; ++t) { const bf16x8s ak = __builtin_shufflevector(fkt[g % 3][t][0], fkt[g % 3][t][1], 0, 1, 2, 3, 4, 5, 6, 7);
; #pragma unroll
;                     for (int ct = 0; ct < 2; ++ct) st[2 * (g & 7) + t][ct] = __builtin_amdgcn_mfma_f32_16x16x32_bf16(ak, bv[g >> 3][ct], st[2 * (g & 7) + t][ct], 0, 0, 0); }
	ds_read_b64_tr_b16 v[178:179], v225 offset:33792
	ds_read_b64_tr_b16 v[182:183], v225 offset:33824
	ds_read_b64_tr_b16 v[186:187], v225 offset:33856
	ds_read_b64_tr_b16 v[190:191], v225 offset:33888
	ds_read_b64_tr_b16 v[180:181], v225 offset:35968
	ds_read_b64_tr_b16 v[184:185], v225 offset:36000
	ds_read_b64_tr_b16 v[188:189], v225 offset:36032
	ds_read_b64_tr_b16 v[192:193], v225 offset:36064
	v_cvt_pk_bf16_f32 v162, v38, v39
	v_cvt_pk_bf16_f32 v163, v40, v41
	v_cvt_pk_bf16_f32 v164, v30, v31
	v_cvt_pk_bf16_f32 v165, v32, v33
	s_nop 1
	v_mfma_f32_16x16x32_bf16 v[158:161], v[162:165], v[194:197], v[150:153]
	v_mfma_f32_16x16x32_bf16 v[154:157], v[162:165], v[198:201], v[154:157]
	v_mfma_f32_16x16x32_bf16 v[150:153], v[162:165], v[202:205], v[166:169]
	v_mfma_f32_16x16x32_bf16 v[146:149], v[162:165], v[244:247], v[146:149]
	v_cvt_pk_bf16_f32 v162, v34, v35
	v_cvt_pk_bf16_f32 v163, v36, v37
	v_cvt_pk_bf16_f32 v164, v2, v3
	v_cvt_pk_bf16_f32 v165, v4, v5
	s_nop 1
	v_mfma_f32_16x16x32_bf16 v[174:177], v[162:165], v[194:197], v[130:133]
	v_mfma_f32_16x16x32_bf16 v[170:173], v[162:165], v[198:201], v[134:137]
	v_mfma_f32_16x16x32_bf16 v[166:169], v[162:165], v[202:205], v[138:141]
	v_mfma_f32_16x16x32_bf16 v[138:141], v[162:165], v[244:247], v[142:145]
	ds_read_b64_tr_b16 v[164:165], v215 offset:1152
	ds_read_b64_tr_b16 v[162:163], v215
	s_nop 0
	ds_read_b64_tr_b16 v[144:145], v215 offset:1184
	ds_read_b64_tr_b16 v[142:143], v215 offset:32
	ds_read_b64_tr_b16 v[130:131], v215 offset:9216
	ds_read_b64_tr_b16 v[132:133], v215 offset:10368
	ds_read_b64_tr_b16 v[136:137], v215 offset:10400
	ds_read_b64_tr_b16 v[134:135], v215 offset:9248
	ds_read_b64_tr_b16 v[196:197], v225 offset:36096
	ds_read_b64_tr_b16 v[194:195], v225 offset:33920
	ds_read_b64_tr_b16 v[200:201], v225 offset:36128
	ds_read_b64_tr_b16 v[198:199], v225 offset:33952
	s_waitcnt lgkmcnt(10)
	v_mfma_f32_16x16x32_bf16 v[126:129], v[178:181], v[162:165], v[126:129]
	s_waitcnt lgkmcnt(8)
	v_mfma_f32_16x16x32_bf16 v[122:125], v[178:181], v[142:145], v[122:125]
	v_mfma_f32_16x16x32_bf16 v[118:121], v[182:185], v[162:165], v[118:121]
	v_mfma_f32_16x16x32_bf16 v[114:117], v[182:185], v[142:145], v[114:117]
	ds_read_b64_tr_b16 v[180:181], v225 offset:36160
	ds_read_b64_tr_b16 v[178:179], v225 offset:33984
	ds_read_b64_tr_b16 v[184:185], v225 offset:36192
	ds_read_b64_tr_b16 v[182:183], v225 offset:34016
	v_mfma_f32_16x16x32_bf16 v[110:113], v[186:189], v[162:165], v[110:113]
	v_mfma_f32_16x16x32_bf16 v[106:109], v[186:189], v[142:145], v[106:109]
	v_mfma_f32_16x16x32_bf16 v[102:105], v[190:193], v[162:165], v[102:105]
	v_mfma_f32_16x16x32_bf16 v[98:101], v[190:193], v[142:145], v[98:101]
	ds_read_b64_tr_b16 v[188:189], v225 offset:36224
	ds_read_b64_tr_b16 v[186:187], v225 offset:34048
	ds_read_b64_tr_b16 v[192:193], v225 offset:36256
	ds_read_b64_tr_b16 v[190:191], v225 offset:34080
	s_waitcnt lgkmcnt(10)
	v_mfma_f32_16x16x32_bf16 v[94:97], v[194:197], v[162:165], v[94:97]
	v_mfma_f32_16x16x32_bf16 v[90:93], v[194:197], v[142:145], v[90:93]
	s_waitcnt lgkmcnt(8)
	v_mfma_f32_16x16x32_bf16 v[86:89], v[198:201], v[162:165], v[86:89]
	v_mfma_f32_16x16x32_bf16 v[82:85], v[198:201], v[142:145], v[82:85]
	ds_read_b64_tr_b16 v[196:197], v225 offset:36288
	ds_read_b64_tr_b16 v[194:195], v225 offset:34112
	ds_read_b64_tr_b16 v[200:201], v225 offset:36320
	ds_read_b64_tr_b16 v[198:199], v225 offset:34144
	s_waitcnt lgkmcnt(10)
	v_mfma_f32_16x16x32_bf16 v[78:81], v[178:181], v[162:165], v[78:81]
	v_mfma_f32_16x16x32_bf16 v[74:77], v[178:181], v[142:145], v[74:77]
	s_waitcnt lgkmcnt(8)
	v_mfma_f32_16x16x32_bf16 v[70:73], v[182:185], v[162:165], v[70:73]
	v_mfma_f32_16x16x32_bf16 v[66:69], v[182:185], v[142:145], v[66:69]
	ds_read_b64_tr_b16 v[180:181], v225 offset:36352
	ds_read_b64_tr_b16 v[178:179], v225 offset:34176
	ds_read_b64_tr_b16 v[184:185], v225 offset:36384
	ds_read_b64_tr_b16 v[182:183], v225 offset:34208
	s_waitcnt lgkmcnt(10)
	v_mfma_f32_16x16x32_bf16 v[54:57], v[186:189], v[162:165], v[54:57]
	v_mfma_f32_16x16x32_bf16 v[50:53], v[186:189], v[142:145], v[50:53]
	s_waitcnt lgkmcnt(8)
	v_mfma_f32_16x16x32_bf16 v[46:49], v[190:193], v[162:165], v[46:49]
	v_mfma_f32_16x16x32_bf16 v[42:45], v[190:193], v[142:145], v[42:45]
	ds_read_b64_tr_b16 v[188:189], v225 offset:36416
	ds_read_b64_tr_b16 v[186:187], v225 offset:34240
	ds_read_b64_tr_b16 v[192:193], v225 offset:36448
	ds_read_b64_tr_b16 v[190:191], v225 offset:34272
	s_waitcnt lgkmcnt(10)
	v_mfma_f32_16x16x32_bf16 v[26:29], v[194:197], v[162:165], v[26:29]
	v_mfma_f32_16x16x32_bf16 v[22:25], v[194:197], v[142:145], v[22:25]
	s_waitcnt lgkmcnt(8)
	v_mfma_f32_16x16x32_bf16 v[18:21], v[198:201], v[162:165], v[18:21]
	v_mfma_f32_16x16x32_bf16 v[14:17], v[198:201], v[142:145], v[14:17]
	ds_read_b64_tr_b16 v[196:197], v225 offset:53376
	ds_read_b64_tr_b16 v[194:195], v225 offset:51200
	ds_read_b64_tr_b16 v[200:201], v225 offset:53408
	ds_read_b64_tr_b16 v[198:199], v225 offset:51232
	s_waitcnt lgkmcnt(8)
	v_mfma_f32_16x16x32_bf16 v[62:65], v[182:185], v[162:165], v[62:65]
	v_mfma_f32_16x16x32_bf16 v[58:61], v[182:185], v[142:145], v[58:61]
	v_mfma_f32_16x16x32_bf16 v[202:205], v[178:181], v[162:165], v[10:13]
	v_mfma_f32_16x16x32_bf16 v[178:181], v[178:181], v[142:145], v[6:9]
	s_nop 2
	ds_read_b64_tr_b16 v[8:9], v225 offset:53440
	ds_read_b64_tr_b16 v[6:7], v225 offset:51264
	ds_read_b64_tr_b16 v[12:13], v225 offset:53472
	ds_read_b64_tr_b16 v[10:11], v225 offset:51296
	s_waitcnt lgkmcnt(10)
	v_mfma_f32_16x16x32_bf16 v[182:185], v[186:189], v[162:165], v[38:41]
	v_mfma_f32_16x16x32_bf16 v[186:189], v[186:189], v[142:145], v[34:37]
	s_waitcnt lgkmcnt(8)
; #define LAS __attribute__((address_space(3)))
; #define SC_BAR() do { asm volatile("s_waitcnt lgkmcnt(0)" ::: "memory"); __builtin_amdgcn_s_barrier(); asm volatile("" ::: "memory"); } while (0)
; #define LD_C2(buf, g) do { const int ks_ = (g) >> 3, t0_ = 2 * ((g) & 7); _Pragma("unroll") for (int t = 0; t < 2; ++t) { \
;                 fkt[buf][t][0] = ldtr(lds + SC_KI + (32 * ks_ + 8 * fq + q4) * SC_KS + (16 * (t0_ + t) + 4 * p4) * 2); \
;                 fkt[buf][t][1] = ldtr(lds + SC_KI + (32 * ks_ + 8 * fq + 4 + q4) * SC_KS + (16 * (t0_ + t) + 4 * p4) * 2); } } while (0)
; template <bool GLA>
; __device__ __forceinline__ void scan_item2(LAS unsigned char* lds, const bf16* Qd, const bf16* Kd, const bf16* V, bf16* O, const float* EG, int ldqk, int ldv, int b, int h, int dvs, float e_const, int tid) {
;     ...
; #pragma unroll
;             for (int g = 0; g < 16; ++g) {
;                 if (g + 2 < 16) LD_C2((g + 2) % 3, g + 2);
;                 __builtin_amdgcn_sched_barrier(0);
; #pragma unroll
;                 for (int t = 0; t < 2; ++t) { const bf16x8s ak = __builtin_shufflevector(fkt[g % 3][t][0], fkt[g % 3][t][1], 0, 1, 2, 3, 4, 5, 6, 7);
; #pragma unroll
;                     for (int ct = 0; ct < 2; ++ct) st[2 * (g & 7) + t][ct] = __builtin_amdgcn_mfma_f32_16x16x32_bf16(ak, bv[g >> 3][ct], st[2 * (g & 7) + t][ct], 0, 0, 0); }
;                 __builtin_amdgcn_sched_barrier(0);
;             }
;     ...
; #pragma unroll
;             for (int t = 0; t < 16; ++t) { if (GLA) { const f32x4 e4 = *(const LAS f32x4*)(lds + SC_EI + (16 * t + 4 * fq) * 4); st[t][0] = st[t][0] * e4; st[t][1] = st[t][1] * e4; } else { st[t][0] = st[t][0] * e_const; st[t][1] = st[t][1] * e_const; } }
;             SC_BAR();
	v_mfma_f32_16x16x32_bf16 v[244:247], v[190:193], v[162:165], v[30:33]
	v_mfma_f32_16x16x32_bf16 v[234:237], v[190:193], v[142:145], v[2:5]
	s_nop 2
	ds_read_b64_tr_b16 v[4:5], v225 offset:53504
	ds_read_b64_tr_b16 v[2:3], v225 offset:51328
	ds_read_b64_tr_b16 v[32:33], v225 offset:53536
	ds_read_b64_tr_b16 v[30:31], v225 offset:51360
	s_waitcnt lgkmcnt(10)
	v_mfma_f32_16x16x32_bf16 v[126:129], v[194:197], v[130:133], v[126:129]
	v_mfma_f32_16x16x32_bf16 v[122:125], v[194:197], v[134:137], v[122:125]
	s_waitcnt lgkmcnt(8)
	v_mfma_f32_16x16x32_bf16 v[118:121], v[198:201], v[130:133], v[118:121]
	v_mfma_f32_16x16x32_bf16 v[114:117], v[198:201], v[134:137], v[114:117]
	ds_read_b64_tr_b16 v[36:37], v225 offset:53568
	ds_read_b64_tr_b16 v[34:35], v225 offset:51392
	ds_read_b64_tr_b16 v[40:41], v225 offset:53600
	ds_read_b64_tr_b16 v[38:39], v225 offset:51424
	s_waitcnt lgkmcnt(10)
	v_mfma_f32_16x16x32_bf16 v[110:113], v[6:9], v[130:133], v[110:113]
	v_mfma_f32_16x16x32_bf16 v[106:109], v[6:9], v[134:137], v[106:109]
	s_waitcnt lgkmcnt(8)
	v_mfma_f32_16x16x32_bf16 v[102:105], v[10:13], v[130:133], v[102:105]
	v_mfma_f32_16x16x32_bf16 v[98:101], v[10:13], v[134:137], v[98:101]
	ds_read_b64_tr_b16 v[8:9], v225 offset:53632
	ds_read_b64_tr_b16 v[6:7], v225 offset:51456
	ds_read_b64_tr_b16 v[12:13], v225 offset:53664
	ds_read_b64_tr_b16 v[10:11], v225 offset:51488
	s_waitcnt lgkmcnt(10)
	v_mfma_f32_16x16x32_bf16 v[94:97], v[2:5], v[130:133], v[94:97]
	v_mfma_f32_16x16x32_bf16 v[90:93], v[2:5], v[134:137], v[90:93]
	s_waitcnt lgkmcnt(8)
	v_mfma_f32_16x16x32_bf16 v[86:89], v[30:33], v[130:133], v[86:89]
	v_mfma_f32_16x16x32_bf16 v[82:85], v[30:33], v[134:137], v[82:85]
	ds_read_b64_tr_b16 v[32:33], v225 offset:53696
	ds_read_b64_tr_b16 v[30:31], v225 offset:51520
	ds_read_b64_tr_b16 v[192:193], v225 offset:53728
	ds_read_b64_tr_b16 v[190:191], v225 offset:51552
	s_waitcnt lgkmcnt(10)
	v_mfma_f32_16x16x32_bf16 v[78:81], v[34:37], v[130:133], v[78:81]
	v_mfma_f32_16x16x32_bf16 v[74:77], v[34:37], v[134:137], v[74:77]
	s_waitcnt lgkmcnt(8)
	v_mfma_f32_16x16x32_bf16 v[70:73], v[38:41], v[130:133], v[70:73]
	v_mfma_f32_16x16x32_bf16 v[66:69], v[38:41], v[134:137], v[66:69]
	ds_read_b64_tr_b16 v[40:41], v225 offset:53760
	ds_read_b64_tr_b16 v[38:39], v225 offset:51584
	ds_read_b64_tr_b16 v[196:197], v225 offset:53792
	ds_read_b64_tr_b16 v[194:195], v225 offset:51616
	s_waitcnt lgkmcnt(10)
	v_mfma_f32_16x16x32_bf16 v[54:57], v[6:9], v[130:133], v[54:57]
	v_mfma_f32_16x16x32_bf16 v[50:53], v[6:9], v[134:137], v[50:53]
	s_waitcnt lgkmcnt(8)
	v_mfma_f32_16x16x32_bf16 v[46:49], v[10:13], v[130:133], v[46:49]
	v_mfma_f32_16x16x32_bf16 v[42:45], v[10:13], v[134:137], v[42:45]
	ds_read_b64_tr_b16 v[200:201], v225 offset:53824
	ds_read_b64_tr_b16 v[198:199], v225 offset:51648
	ds_read_b64_tr_b16 v[240:241], v225 offset:53856
	ds_read_b64_tr_b16 v[238:239], v225 offset:51680
	s_waitcnt lgkmcnt(10)
	v_mfma_f32_16x16x32_bf16 v[2:5], v[30:33], v[130:133], v[26:29]
	v_mfma_f32_16x16x32_bf16 v[6:9], v[30:33], v[134:137], v[22:25]
	s_waitcnt lgkmcnt(8)
	v_mfma_f32_16x16x32_bf16 v[10:13], v[190:193], v[130:133], v[18:21]
	v_mfma_f32_16x16x32_bf16 v[14:17], v[190:193], v[134:137], v[14:17]
	s_waitcnt lgkmcnt(6)
	v_mfma_f32_16x16x32_bf16 v[34:37], v[38:41], v[130:133], v[202:205]
	v_mfma_f32_16x16x32_bf16 v[30:33], v[38:41], v[134:137], v[178:181]
	s_waitcnt lgkmcnt(4)
	v_mfma_f32_16x16x32_bf16 v[38:41], v[194:197], v[130:133], v[62:65]
	v_mfma_f32_16x16x32_bf16 v[58:61], v[194:197], v[134:137], v[58:61]
	s_waitcnt lgkmcnt(2)
	v_mfma_f32_16x16x32_bf16 v[178:181], v[198:201], v[130:133], v[182:185]
	v_mfma_f32_16x16x32_bf16 v[182:185], v[198:201], v[134:137], v[186:189]
	s_waitcnt lgkmcnt(0)
	v_mfma_f32_16x16x32_bf16 v[190:193], v[238:241], v[130:133], v[244:247]
	v_mfma_f32_16x16x32_bf16 v[186:189], v[238:241], v[134:137], v[234:237]
	s_waitcnt lgkmcnt(0)
	s_barrier
; #define LAS __attribute__((address_space(3)))
; __device__ __forceinline__ unsigned cvt2(float a, float b) { f32x2s v = {a, b}; bf16x2_t r = __builtin_convertvector(v, bf16x2_t); return __builtin_bit_cast(unsigned, r); }
; #define SC_BAR() do { asm volatile("s_waitcnt lgkmcnt(0)" ::: "memory"); __builtin_amdgcn_s_barrier(); asm volatile("" ::: "memory"); } while (0)
; template <bool GLA>
; __device__ __forceinline__ void scan_item2(LAS unsigned char* lds, const bf16* Qd, const bf16* Kd, const bf16* V, bf16* O, const float* EG, int ldqk, int ldv, int b, int h, int dvs, float e_const, int tid) {
;     ...
;             for (int t = 0; t < 16; ++t) { if (GLA) { const f32x4 e4 = *(const LAS f32x4*)(lds + SC_EI + (16 * t + 4 * fq) * 4); st[t][0] = st[t][0] * e4; st[t][1] = st[t][1] * e4; } else { st[t][0] = st[t][0] * e_const; st[t][1] = st[t][1] * e_const; } }
;             SC_BAR();
; #pragma unroll
;             for (int ks = 0; ks < 2; ++ks) { bf16x8s ap[4];
; #pragma unroll
;                 for (int ti = 0; ti < 4; ++ti) ap[ti] = *(const LAS bf16x8s*)(lds + SC_PI + (16 * ti + fr) * SC_PS + (32 * ks + 8 * fq) * 2);
; #pragma unroll
;                 for (int ti = 0; ti < 4; ++ti)
; #pragma unroll
;                     for (int ct = 0; ct < 2; ++ct) oa[ti][ct] = __builtin_amdgcn_mfma_f32_16x16x32_bf16(bv[ks][ct], ap[ti], oa[ti][ct], 0, 0, 0); }
; #pragma unroll
;             for (int ti = 0; ti < 4; ++ti)
; #pragma unroll
;                 for (int ct = 0; ct < 2; ++ct) { v2u ow; ow.x = cvt2(oa[ti][ct][0], oa[ti][ct][1]); ow.y = cvt2(oa[ti][ct][2], oa[ti][ct][3]);
;                     *(v2u*)((char*)(obase + ((size_t)c * 64 + 16 * ti) * ldv + 16 * ct) + ooff) = ow; }
;         }
;         SC_BAR();
	v_pk_mul_f32 v[22:23], v[220:221], v[6:7]
	v_pk_mul_f32 v[6:7], v[220:221], v[30:31]
	ds_read_b128 v[28:31], v249
	ds_read_b128 v[194:197], v249 offset:64
	s_waitcnt lgkmcnt(1)
	v_mfma_f32_16x16x32_bf16 v[198:201], v[162:165], v[28:31], v[158:161]
	ds_read_b128 v[234:237], v249 offset:5120
	s_nop 1
	ds_read_b128 v[158:161], v249 offset:2624
	v_mov_b32_e32 v219, v218
	v_mfma_f32_16x16x32_bf16 v[174:177], v[142:145], v[28:31], v[174:177]
	ds_read_b128 v[28:31], v249 offset:2560
	v_pk_mul_f32 v[62:63], v[220:221], v[38:39]
	v_pk_mul_f32 v[38:39], v[220:221], v[178:179]
	s_waitcnt lgkmcnt(0)
	v_mfma_f32_16x16x32_bf16 v[202:205], v[162:165], v[28:31], v[154:157]
	v_lshl_add_u64 v[178:179], v[222:223], 0, s[6:7]
	s_nop 1
	ds_read_b128 v[154:157], v249 offset:5184
	s_mov_b32 s0, 0x39f00000
	v_mfma_f32_16x16x32_bf16 v[238:241], v[162:165], v[234:237], v[150:153]
	v_mul_f32_e64 v64, v218, v40
	v_mul_f32_e64 v65, v219, v41
	v_pk_mul_f32 v[40:41], v[218:219], v[180:181]
	v_add_co_u32_e32 v180, vcc, s0, v178
	v_mfma_f32_16x16x32_bf16 v[166:169], v[142:145], v[234:237], v[166:169]
	ds_read_b128 v[234:237], v249 offset:7680
	ds_read_b128 v[150:153], v249 offset:7744
	s_mov_b32 s1, 0x39f20000
	v_mfma_f32_16x16x32_bf16 v[170:173], v[142:145], v[28:31], v[170:173]
	v_addc_co_u32_e32 v181, vcc, 0, v179, vcc
	v_pk_mul_f32 v[18:19], v[220:221], v[10:11]
	s_waitcnt lgkmcnt(1)
	v_mfma_f32_16x16x32_bf16 v[146:149], v[162:165], v[234:237], v[146:149]
	v_mul_f32_e64 v10, v220, v34
	v_mul_f32_e64 v11, v221, v35
	v_pk_mul_f32 v[34:35], v[220:221], v[182:183]
	v_add_co_u32_e32 v182, vcc, s1, v178
	v_mfma_f32_16x16x32_bf16 v[138:141], v[142:145], v[234:237], v[138:141]
	s_mov_b32 s11, 0x39f40000
	v_addc_co_u32_e32 v183, vcc, 0, v179, vcc
	v_mfma_f32_16x16x32_bf16 v[142:145], v[130:133], v[194:197], v[198:201]
	s_add_u32 s6, s6, 0x80000
	v_pk_mul_f32 v[20:21], v[218:219], v[12:13]
	v_pk_mul_f32 v[12:13], v[218:219], v[36:37]
	v_mfma_f32_16x16x32_bf16 v[162:165], v[134:137], v[194:197], v[174:177]
	v_mul_f32_e64 v36, v218, v184
	v_mul_f32_e64 v37, v219, v185
	v_add_co_u32_e32 v184, vcc, s11, v178
	v_mfma_f32_16x16x32_bf16 v[174:177], v[130:133], v[158:161], v[202:205]
	s_mov_b32 s12, 0x39f60000
	v_addc_co_u32_e32 v185, vcc, 0, v179, vcc
	v_mfma_f32_16x16x32_bf16 v[158:161], v[134:137], v[158:161], v[170:173]
	s_addc_u32 s7, s7, 0
	v_pk_mul_f32 v[126:127], v[220:221], v[126:127]
	v_pk_mul_f32 v[122:123], v[220:221], v[122:123]
	v_mfma_f32_16x16x32_bf16 v[170:173], v[130:133], v[154:157], v[238:241]
	v_mul_f32_e64 v118, v220, v118
	v_mul_f32_e64 v119, v221, v119
	v_pk_mul_f32 v[114:115], v[220:221], v[114:115]
	v_pk_mul_f32 v[110:111], v[220:221], v[110:111]
	v_mfma_f32_16x16x32_bf16 v[154:157], v[134:137], v[154:157], v[166:169]
	v_mul_f32_e64 v106, v220, v106
	v_mul_f32_e64 v107, v221, v107
	v_pk_mul_f32 v[102:103], v[220:221], v[102:103]
	v_pk_mul_f32 v[98:99], v[220:221], v[98:99]
	s_waitcnt lgkmcnt(0)
	v_mfma_f32_16x16x32_bf16 v[130:133], v[130:133], v[150:153], v[146:149]
	v_mul_f32_e64 v94, v220, v94
	v_mul_f32_e64 v95, v221, v95
	v_pk_mul_f32 v[90:91], v[220:221], v[90:91]
	v_pk_mul_f32 v[86:87], v[220:221], v[86:87]
	v_mfma_f32_16x16x32_bf16 v[134:137], v[134:137], v[150:153], v[138:141]
	v_mul_f32_e64 v82, v220, v82
	v_mul_f32_e64 v83, v221, v83
	v_pk_mul_f32 v[78:79], v[220:221], v[78:79]
	v_pk_mul_f32 v[74:75], v[220:221], v[74:75]
	v_pk_mul_f32 v[70:71], v[220:221], v[70:71]
	v_pk_mul_f32 v[66:67], v[220:221], v[66:67]
	v_pk_mul_f32 v[54:55], v[220:221], v[54:55]
	v_pk_mul_f32 v[128:129], v[218:219], v[128:129]
	v_pk_mul_f32 v[50:51], v[220:221], v[50:51]
	v_pk_mul_f32 v[124:125], v[218:219], v[124:125]
	v_pk_mul_f32 v[46:47], v[220:221], v[46:47]
	v_pk_mul_f32 v[120:121], v[218:219], v[120:121]
	v_pk_mul_f32 v[42:43], v[220:221], v[42:43]
	v_pk_mul_f32 v[116:117], v[218:219], v[116:117]
	v_pk_mul_f32 v[26:27], v[220:221], v[2:3]
	v_pk_mul_f32 v[112:113], v[218:219], v[112:113]
	v_pk_mul_f32 v[108:109], v[218:219], v[108:109]
	v_pk_mul_f32 v[104:105], v[218:219], v[104:105]
	v_pk_mul_f32 v[14:15], v[220:221], v[14:15]
	v_pk_mul_f32 v[100:101], v[218:219], v[100:101]
	v_pk_mul_f32 v[96:97], v[218:219], v[96:97]
	v_pk_mul_f32 v[92:93], v[218:219], v[92:93]
	v_pk_mul_f32 v[88:89], v[218:219], v[88:89]
	v_pk_mul_f32 v[84:85], v[218:219], v[84:85]
	v_pk_mul_f32 v[80:81], v[218:219], v[80:81]
	v_pk_mul_f32 v[58:59], v[220:221], v[58:59]
	v_pk_mul_f32 v[76:77], v[218:219], v[76:77]
	v_pk_mul_f32 v[72:73], v[218:219], v[72:73]
	v_pk_mul_f32 v[68:69], v[218:219], v[68:69]
	v_pk_mul_f32 v[56:57], v[218:219], v[56:57]
	v_pk_mul_f32 v[52:53], v[218:219], v[52:53]
	v_pk_mul_f32 v[30:31], v[220:221], v[190:191]
	v_pk_mul_f32 v[48:49], v[218:219], v[48:49]
	v_pk_mul_f32 v[2:3], v[220:221], v[186:187]
	v_pk_mul_f32 v[44:45], v[218:219], v[44:45]
	v_pk_mul_f32 v[28:29], v[218:219], v[4:5]
	v_pk_mul_f32 v[24:25], v[218:219], v[8:9]
	v_pk_mul_f32 v[16:17], v[218:219], v[16:17]
	v_pk_mul_f32 v[8:9], v[218:219], v[32:33]
	v_pk_mul_f32 v[60:61], v[218:219], v[60:61]
	v_pk_mul_f32 v[32:33], v[218:219], v[192:193]
	v_pk_mul_f32 v[4:5], v[218:219], v[188:189]
	v_add_co_u32_e32 v166, vcc, s12, v178
	s_cmp_eq_u32 s6, 0x1000000
	v_cvt_pk_bf16_f32 v138, v142, v143
	v_cvt_pk_bf16_f32 v139, v144, v145
	v_addc_co_u32_e32 v167, vcc, 0, v179, vcc
	v_cvt_pk_bf16_f32 v140, v162, v163
	v_cvt_pk_bf16_f32 v141, v164, v165
	v_cvt_pk_bf16_f32 v142, v174, v175
	v_cvt_pk_bf16_f32 v143, v176, v177
	v_cvt_pk_bf16_f32 v144, v158, v159
	v_cvt_pk_bf16_f32 v145, v160, v161
	v_cvt_pk_bf16_f32 v146, v170, v171
	v_cvt_pk_bf16_f32 v147, v172, v173
	v_cvt_pk_bf16_f32 v148, v154, v155
	v_cvt_pk_bf16_f32 v149, v156, v157
	v_cvt_pk_bf16_f32 v130, v130, v131
	v_cvt_pk_bf16_f32 v131, v132, v133
	v_cvt_pk_bf16_f32 v132, v134, v135
	v_cvt_pk_bf16_f32 v133, v136, v137
	global_store_dwordx2 v[180:181], v[138:139], off
	global_store_dwordx2 v[180:181], v[140:141], off offset:32
	global_store_dwordx2 v[182:183], v[142:143], off
	global_store_dwordx2 v[182:183], v[144:145], off offset:32
	global_store_dwordx2 v[184:185], v[146:147], off
	global_store_dwordx2 v[184:185], v[148:149], off offset:32
	global_store_dwordx2 v[166:167], v[130:131], off
	global_store_dwordx2 v[166:167], v[132:133], off offset:32
	s_cbranch_scc0 .LBB0_415
	s_setprio 0
	s_waitcnt lgkmcnt(0)
	s_barrier
	s_branch .LBB0_411

; __device__ __forceinline__ unsigned cvt2(float a, float b) { f32x2s v = {a, b}; bf16x2_t r = __builtin_convertvector(v, bf16x2_t); return __builtin_bit_cast(unsigned, r); }
; #define SC_BAR() do { asm volatile("s_waitcnt lgkmcnt(0)" ::: "memory"); __builtin_amdgcn_s_barrier(); asm volatile("" ::: "memory"); } while (0)
; template <bool GLA>
; __device__ __forceinline__ void scan_item2(LAS unsigned char* lds, const bf16* Qd, const bf16* Kd, const bf16* V, bf16* O, const float* EG, int ldqk, int ldv, int b, int h, int dvs, float e_const, int tid) {
;     ...
;         f32x4 st[16][2];
; #pragma unroll
;         for (int t = 0; t < 16; ++t) { st[t][0] = (f32x4){0.f, 0.f, 0.f, 0.f}; st[t][1] = (f32x4){0.f, 0.f, 0.f, 0.f}; }
;         bf16* const obase = O + (size_t)(b * SEQ) * ldv + h * 512 + dvs * 128 + 32 * w;
;         const unsigned ooff = (unsigned)(fr * ldv + 4 * fq) * 2u;
;         for (int c = 0; c < SEQ / 64; ++c) {
;             SC_BAR();
;             f32x4 oa[4][2];
; #pragma unroll
;             for (int ti = 0; ti < 4; ++ti) { oa[ti][0] = (f32x4){0.f, 0.f, 0.f, 0.f}; oa[ti][1] = (f32x4){0.f, 0.f, 0.f, 0.f}; }
;             v2u faq[2][4][2];
;     ...
;             s16x4 fkt[3][2][2]; bf16x8s bv[2][2];
;     ...
;             LD_C1(0, 0);
; #pragma unroll
;             for (int s_ = 0; s_ < 8; ++s_) {
;                 if (s_ + 1 < 8) LD_C1((s_ + 1) & 1, s_ + 1); else { LD_C2(0, 0); LD_C2(1, 1); }
;                 __builtin_amdgcn_sched_barrier(0);
; #pragma unroll
;                 for (int ct = 0; ct < 2; ++ct) {
;                     v4u sbw; sbw.x = cvt2(st[2 * s_][ct][0], st[2 * s_][ct][1]); sbw.y = cvt2(st[2 * s_][ct][2], st[2 * s_][ct][3]); sbw.z = cvt2(st[2 * s_ + 1][ct][0], st[2 * s_ + 1][ct][1]); sbw.w = cvt2(st[2 * s_ + 1][ct][2], st[2 * s_ + 1][ct][3]);
;                     const bf16x8s sb = __builtin_bit_cast(bf16x8s, sbw);
; #pragma unroll
;                     for (int ti = 0; ti < 4; ++ti) { v4u aw; aw.x = faq[s_ & 1][ti][0].x; aw.y = faq[s_ & 1][ti][0].y; aw.z = faq[s_ & 1][ti][1].x; aw.w = faq[s_ & 1][ti][1].y;
;                         oa[ti][ct] = __builtin_amdgcn_mfma_f32_16x16x32_bf16(sb, __builtin_bit_cast(bf16x8s, aw), oa[ti][ct], 0, 0, 0); } }
.LBB0_1910:
	s_ashr_i32 s9, s8, 31
	s_lshl_b64 s[0:1], s[8:9], 12
	s_lshl_b32 s10, s12, 5
	s_and_b32 s9, s87, 0xc00
	s_ashr_i32 s11, s10, 31
	s_or_b32 s0, s0, s9
	s_andn2_b32 s15, s15, 63
	s_or_b64 s[0:1], s[0:1], s[66:67]
	s_lshl_b64 s[10:11], s[10:11], 1
	s_add_u32 s0, s0, s10
	v_or_b32_e32 v1, s15, v193
	s_addc_u32 s1, s1, s11
	v_mov_b32_e32 v122, 0
	v_lshl_add_u64 v[190:191], v[184:185], 0, s[0:1]
	s_mov_b64 s[10:11], 0
	v_add_u32_e32 v1, v195, v1
	v_mov_b32_e32 v123, v122
	v_mov_b32_e32 v124, v122
	v_mov_b32_e32 v125, v122
	v_mov_b32_e32 v126, v122
	v_mov_b32_e32 v127, v122
	v_mov_b32_e32 v128, v122
	v_mov_b32_e32 v129, v122
	v_mov_b32_e32 v114, v122
	v_mov_b32_e32 v115, v122
	v_mov_b32_e32 v116, v122
	v_mov_b32_e32 v117, v122
	v_mov_b32_e32 v118, v122
	v_mov_b32_e32 v119, v122
	v_mov_b32_e32 v120, v122
	v_mov_b32_e32 v121, v122
	v_mov_b32_e32 v106, v122
	v_mov_b32_e32 v107, v122
	v_mov_b32_e32 v108, v122
	v_mov_b32_e32 v109, v122
	v_mov_b32_e32 v110, v122
	v_mov_b32_e32 v111, v122
	v_mov_b32_e32 v112, v122
	v_mov_b32_e32 v113, v122
	v_mov_b32_e32 v98, v122
	v_mov_b32_e32 v99, v122
	v_mov_b32_e32 v100, v122
	v_mov_b32_e32 v101, v122
	v_mov_b32_e32 v102, v122
	v_mov_b32_e32 v103, v122
	v_mov_b32_e32 v104, v122
	v_mov_b32_e32 v105, v122
	v_mov_b32_e32 v90, v122
	v_mov_b32_e32 v91, v122
	v_mov_b32_e32 v92, v122
	v_mov_b32_e32 v93, v122
	v_mov_b32_e32 v94, v122
	v_mov_b32_e32 v95, v122
	v_mov_b32_e32 v96, v122
	v_mov_b32_e32 v97, v122
	v_mov_b32_e32 v82, v122
	v_mov_b32_e32 v83, v122
	v_mov_b32_e32 v84, v122
	v_mov_b32_e32 v85, v122
	v_mov_b32_e32 v86, v122
	v_mov_b32_e32 v87, v122
	v_mov_b32_e32 v88, v122
	v_mov_b32_e32 v89, v122
	v_mov_b32_e32 v74, v122
	v_mov_b32_e32 v75, v122
	v_mov_b32_e32 v76, v122
	v_mov_b32_e32 v77, v122
	v_mov_b32_e32 v78, v122
	v_mov_b32_e32 v79, v122
	v_mov_b32_e32 v80, v122
	v_mov_b32_e32 v81, v122
	v_mov_b32_e32 v66, v122
	v_mov_b32_e32 v67, v122
	v_mov_b32_e32 v68, v122
	v_mov_b32_e32 v69, v122
	v_mov_b32_e32 v70, v122
	v_mov_b32_e32 v71, v122
	v_mov_b32_e32 v72, v122
	v_mov_b32_e32 v73, v122
	v_mov_b32_e32 v58, v122
	v_mov_b32_e32 v59, v122
	v_mov_b32_e32 v60, v122
	v_mov_b32_e32 v61, v122
	v_mov_b32_e32 v62, v122
	v_mov_b32_e32 v63, v122
	v_mov_b32_e32 v64, v122
	v_mov_b32_e32 v65, v122
	v_mov_b32_e32 v50, v122
	v_mov_b32_e32 v51, v122
	v_mov_b32_e32 v52, v122
	v_mov_b32_e32 v53, v122
	v_mov_b32_e32 v54, v122
	v_mov_b32_e32 v55, v122
	v_mov_b32_e32 v56, v122
	v_mov_b32_e32 v57, v122
	v_mov_b32_e32 v42, v122
	v_mov_b32_e32 v43, v122
	v_mov_b32_e32 v44, v122
	v_mov_b32_e32 v45, v122
	v_mov_b32_e32 v46, v122
	v_mov_b32_e32 v47, v122
	v_mov_b32_e32 v48, v122
	v_mov_b32_e32 v49, v122
	v_mov_b32_e32 v34, v122
	v_mov_b32_e32 v35, v122
	v_mov_b32_e32 v36, v122
	v_mov_b32_e32 v37, v122
	v_mov_b32_e32 v38, v122
	v_mov_b32_e32 v39, v122
	v_mov_b32_e32 v40, v122
	v_mov_b32_e32 v41, v122
	v_mov_b32_e32 v26, v122
	v_mov_b32_e32 v27, v122
	v_mov_b32_e32 v28, v122
	v_mov_b32_e32 v29, v122
	v_mov_b32_e32 v30, v122
	v_mov_b32_e32 v31, v122
	v_mov_b32_e32 v32, v122
	v_mov_b32_e32 v33, v122
	v_mov_b32_e32 v18, v122
	v_mov_b32_e32 v19, v122
	v_mov_b32_e32 v20, v122
	v_mov_b32_e32 v21, v122
	v_mov_b32_e32 v22, v122
	v_mov_b32_e32 v23, v122
	v_mov_b32_e32 v24, v122
	v_mov_b32_e32 v25, v122
	v_mov_b32_e32 v10, v122
	v_mov_b32_e32 v11, v122
	v_mov_b32_e32 v12, v122
	v_mov_b32_e32 v13, v122
	v_mov_b32_e32 v14, v122
	v_mov_b32_e32 v15, v122
	v_mov_b32_e32 v16, v122
	v_mov_b32_e32 v17, v122
	v_mov_b32_e32 v2, v122
	v_mov_b32_e32 v3, v122
	v_mov_b32_e32 v4, v122
	v_mov_b32_e32 v5, v122
	v_mov_b32_e32 v6, v122
	v_mov_b32_e32 v7, v122
	v_mov_b32_e32 v8, v122
	v_mov_b32_e32 v9, v122
	s_setprio 2
.LBB0_1911:
	s_waitcnt lgkmcnt(0)
	s_barrier
	ds_read2_b64 v[130:133], v217 offset1:4
	ds_read2_b64 v[134:137], v221 offset0:32 offset1:36
	ds_read2_b64 v[138:141], v222 offset0:64 offset1:68
	ds_read2_b64 v[142:145], v223 offset0:96 offset1:100
	ds_read2_b64 v[146:149], v217 offset0:8 offset1:12
	ds_read2_b64 v[150:153], v221 offset0:40 offset1:44
	ds_read2_b64 v[154:157], v222 offset0:72 offset1:76
	ds_read2_b64 v[158:161], v223 offset0:104 offset1:108
	v_cvt_pk_bf16_f32 v162, v6, v7
	v_cvt_pk_bf16_f32 v163, v8, v9
	v_cvt_pk_bf16_f32 v164, v14, v15
	v_cvt_pk_bf16_f32 v165, v16, v17
	v_cvt_pk_bf16_f32 v228, v2, v3
	v_cvt_pk_bf16_f32 v229, v4, v5
	v_cvt_pk_bf16_f32 v230, v10, v11
	v_cvt_pk_bf16_f32 v231, v12, v13
	s_waitcnt lgkmcnt(0)
	v_mfma_f32_16x16x32_bf16 v[166:169], v[162:165], v[130:133], 0
	v_mfma_f32_16x16x32_bf16 v[170:173], v[162:165], v[134:137], 0
	v_mfma_f32_16x16x32_bf16 v[174:177], v[162:165], v[138:141], 0
	v_mfma_f32_16x16x32_bf16 v[162:165], v[162:165], v[142:145], 0
	v_mfma_f32_16x16x32_bf16 v[130:133], v[228:231], v[130:133], 0
	v_mfma_f32_16x16x32_bf16 v[134:137], v[228:231], v[134:137], 0
	v_mfma_f32_16x16x32_bf16 v[138:141], v[228:231], v[138:141], 0
	v_mfma_f32_16x16x32_bf16 v[142:145], v[228:231], v[142:145], 0
	ds_read2_b64 v[228:231], v217 offset0:16 offset1:20
	ds_read2_b64 v[232:235], v221 offset0:48 offset1:52
	ds_read2_b64 v[236:239], v222 offset0:80 offset1:84
	ds_read2_b64 v[240:243], v223 offset0:112 offset1:116
	v_cvt_pk_bf16_f32 v244, v22, v23
	v_cvt_pk_bf16_f32 v245, v24, v25
	v_cvt_pk_bf16_f32 v246, v30, v31
	v_cvt_pk_bf16_f32 v247, v32, v33
	s_nop 1
	v_mfma_f32_16x16x32_bf16 v[166:169], v[244:247], v[146:149], v[166:169]
	v_mfma_f32_16x16x32_bf16 v[170:173], v[244:247], v[150:153], v[170:173]
	v_mfma_f32_16x16x32_bf16 v[174:177], v[244:247], v[154:157], v[174:177]
	v_mfma_f32_16x16x32_bf16 v[162:165], v[244:247], v[158:161], v[162:165]
	v_cvt_pk_bf16_f32 v244, v18, v19
	v_cvt_pk_bf16_f32 v245, v20, v21
	v_cvt_pk_bf16_f32 v246, v26, v27
	v_cvt_pk_bf16_f32 v247, v28, v29
	s_nop 1
	v_mfma_f32_16x16x32_bf16 v[130:133], v[244:247], v[146:149], v[130:133]
	v_mfma_f32_16x16x32_bf16 v[134:137], v[244:247], v[150:153], v[134:137]
	v_mfma_f32_16x16x32_bf16 v[138:141], v[244:247], v[154:157], v[138:141]
	v_mfma_f32_16x16x32_bf16 v[142:145], v[244:247], v[158:161], v[142:145]
	ds_read2_b64 v[146:149], v217 offset0:24 offset1:28
	ds_read2_b64 v[150:153], v221 offset0:56 offset1:60
	ds_read2_b64 v[154:157], v222 offset0:88 offset1:92
	ds_read2_b64 v[158:161], v223 offset0:120 offset1:124
	v_cvt_pk_bf16_f32 v244, v38, v39
	v_cvt_pk_bf16_f32 v245, v40, v41
	v_cvt_pk_bf16_f32 v246, v46, v47
	v_cvt_pk_bf16_f32 v247, v48, v49
	s_waitcnt lgkmcnt(0)
; __device__ __forceinline__ unsigned cvt2(float a, float b) { f32x2s v = {a, b}; bf16x2_t r = __builtin_convertvector(v, bf16x2_t); return __builtin_bit_cast(unsigned, r); }
; #define LD_C1(buf, s_) do { _Pragma("unroll") for (int ti = 0; ti < 4; ++ti) { LAS const unsigned char* ap_ = lds + SC_QI + (16 * ti + fr) * SC_QS + (32 * (s_) + 4 * fq) * 2; \
;                 faq[buf][ti][0] = *(const LAS v2u*)ap_; faq[buf][ti][1] = *(const LAS v2u*)(ap_ + 32); } } while (0)
; #define LD_C2(buf, g) do { const int ks_ = (g) >> 3, t0_ = 2 * ((g) & 7); _Pragma("unroll") for (int t = 0; t < 2; ++t) { \
;                 fkt[buf][t][0] = ldtr(lds + SC_KI + (32 * ks_ + 8 * fq + q4) * SC_KS + (16 * (t0_ + t) + 4 * p4) * 2); \
;                 fkt[buf][t][1] = ldtr(lds + SC_KI + (32 * ks_ + 8 * fq + 4 + q4) * SC_KS + (16 * (t0_ + t) + 4 * p4) * 2); } } while (0)
; template <bool GLA>
; __device__ __forceinline__ void scan_item2(LAS unsigned char* lds, const bf16* Qd, const bf16* Kd, const bf16* V, bf16* O, const float* EG, int ldqk, int ldv, int b, int h, int dvs, float e_const, int tid) {
;     ...
;             for (int s_ = 0; s_ < 8; ++s_) {
;                 if (s_ + 1 < 8) LD_C1((s_ + 1) & 1, s_ + 1); else { LD_C2(0, 0); LD_C2(1, 1); }
;                 __builtin_amdgcn_sched_barrier(0);
; #pragma unroll
;                 for (int ct = 0; ct < 2; ++ct) {
;                     v4u sbw; sbw.x = cvt2(st[2 * s_][ct][0], st[2 * s_][ct][1]); sbw.y = cvt2(st[2 * s_][ct][2], st[2 * s_][ct][3]); sbw.z = cvt2(st[2 * s_ + 1][ct][0], st[2 * s_ + 1][ct][1]); sbw.w = cvt2(st[2 * s_ + 1][ct][2], st[2 * s_ + 1][ct][3]);
;                     const bf16x8s sb = __builtin_bit_cast(bf16x8s, sbw);
; #pragma unroll
;                     for (int ti = 0; ti < 4; ++ti) { v4u aw; aw.x = faq[s_ & 1][ti][0].x; aw.y = faq[s_ & 1][ti][0].y; aw.z = faq[s_ & 1][ti][1].x; aw.w = faq[s_ & 1][ti][1].y;
;                         oa[ti][ct] = __builtin_amdgcn_mfma_f32_16x16x32_bf16(sb, __builtin_bit_cast(bf16x8s, aw), oa[ti][ct], 0, 0, 0); } }
	s_nop 0
	v_mfma_f32_16x16x32_bf16 v[166:169], v[244:247], v[228:231], v[166:169]
	v_mfma_f32_16x16x32_bf16 v[170:173], v[244:247], v[232:235], v[170:173]
	v_mfma_f32_16x16x32_bf16 v[174:177], v[244:247], v[236:239], v[174:177]
	v_mfma_f32_16x16x32_bf16 v[162:165], v[244:247], v[240:243], v[162:165]
	v_cvt_pk_bf16_f32 v244, v34, v35
	v_cvt_pk_bf16_f32 v245, v36, v37
	v_cvt_pk_bf16_f32 v246, v42, v43
	v_cvt_pk_bf16_f32 v247, v44, v45
	s_nop 1
	v_mfma_f32_16x16x32_bf16 v[130:133], v[244:247], v[228:231], v[130:133]
	v_mfma_f32_16x16x32_bf16 v[134:137], v[244:247], v[232:235], v[134:137]
	v_mfma_f32_16x16x32_bf16 v[138:141], v[244:247], v[236:239], v[138:141]
	v_mfma_f32_16x16x32_bf16 v[142:145], v[244:247], v[240:243], v[142:145]
	ds_read2_b64 v[228:231], v217 offset0:32 offset1:36
	ds_read2_b64 v[232:235], v221 offset0:64 offset1:68
	ds_read2_b64 v[236:239], v222 offset0:96 offset1:100
	ds_read2_b64 v[240:243], v223 offset0:128 offset1:132
	v_cvt_pk_bf16_f32 v244, v54, v55
	v_cvt_pk_bf16_f32 v245, v56, v57
	v_cvt_pk_bf16_f32 v246, v62, v63
	v_cvt_pk_bf16_f32 v247, v64, v65
	s_nop 1
	v_mfma_f32_16x16x32_bf16 v[166:169], v[244:247], v[146:149], v[166:169]
	v_mfma_f32_16x16x32_bf16 v[170:173], v[244:247], v[150:153], v[170:173]
	v_mfma_f32_16x16x32_bf16 v[174:177], v[244:247], v[154:157], v[174:177]
	v_mfma_f32_16x16x32_bf16 v[162:165], v[244:247], v[158:161], v[162:165]
	v_cvt_pk_bf16_f32 v244, v50, v51
	v_cvt_pk_bf16_f32 v245, v52, v53
	v_cvt_pk_bf16_f32 v246, v58, v59
	v_cvt_pk_bf16_f32 v247, v60, v61
	s_nop 1
	v_mfma_f32_16x16x32_bf16 v[130:133], v[244:247], v[146:149], v[130:133]
	v_mfma_f32_16x16x32_bf16 v[134:137], v[244:247], v[150:153], v[134:137]
	v_mfma_f32_16x16x32_bf16 v[138:141], v[244:247], v[154:157], v[138:141]
	v_mfma_f32_16x16x32_bf16 v[142:145], v[244:247], v[158:161], v[142:145]
	ds_read2_b64 v[146:149], v217 offset0:40 offset1:44
	ds_read2_b64 v[150:153], v221 offset0:72 offset1:76
	ds_read2_b64 v[154:157], v222 offset0:104 offset1:108
	ds_read2_b64 v[158:161], v223 offset0:136 offset1:140
	v_cvt_pk_bf16_f32 v244, v70, v71
	v_cvt_pk_bf16_f32 v245, v72, v73
	v_cvt_pk_bf16_f32 v246, v78, v79
	v_cvt_pk_bf16_f32 v247, v80, v81
	s_waitcnt lgkmcnt(0)
	s_nop 0
	v_mfma_f32_16x16x32_bf16 v[166:169], v[244:247], v[228:231], v[166:169]
	v_mfma_f32_16x16x32_bf16 v[170:173], v[244:247], v[232:235], v[170:173]
	v_mfma_f32_16x16x32_bf16 v[174:177], v[244:247], v[236:239], v[174:177]
	v_mfma_f32_16x16x32_bf16 v[162:165], v[244:247], v[240:243], v[162:165]
	v_cvt_pk_bf16_f32 v244, v66, v67
	v_cvt_pk_bf16_f32 v245, v68, v69
	v_cvt_pk_bf16_f32 v246, v74, v75
	v_cvt_pk_bf16_f32 v247, v76, v77
	s_nop 1
	v_mfma_f32_16x16x32_bf16 v[130:133], v[244:247], v[228:231], v[130:133]
	v_mfma_f32_16x16x32_bf16 v[134:137], v[244:247], v[232:235], v[134:137]
	v_mfma_f32_16x16x32_bf16 v[138:141], v[244:247], v[236:239], v[138:141]
	v_mfma_f32_16x16x32_bf16 v[142:145], v[244:247], v[240:243], v[142:145]
	ds_read2_b64 v[228:231], v217 offset0:48 offset1:52
	ds_read2_b64 v[232:235], v221 offset0:80 offset1:84
	ds_read2_b64 v[236:239], v222 offset0:112 offset1:116
	ds_read2_b64 v[240:243], v223 offset0:144 offset1:148
	v_cvt_pk_bf16_f32 v244, v86, v87
	v_cvt_pk_bf16_f32 v245, v88, v89
	v_cvt_pk_bf16_f32 v246, v94, v95
	v_cvt_pk_bf16_f32 v247, v96, v97
	s_nop 1
	v_mfma_f32_16x16x32_bf16 v[166:169], v[244:247], v[146:149], v[166:169]
	v_mfma_f32_16x16x32_bf16 v[170:173], v[244:247], v[150:153], v[170:173]
	v_mfma_f32_16x16x32_bf16 v[174:177], v[244:247], v[154:157], v[174:177]
	v_mfma_f32_16x16x32_bf16 v[162:165], v[244:247], v[158:161], v[162:165]
	v_cvt_pk_bf16_f32 v244, v82, v83
	v_cvt_pk_bf16_f32 v245, v84, v85
	v_cvt_pk_bf16_f32 v246, v90, v91
	v_cvt_pk_bf16_f32 v247, v92, v93
	s_nop 1
	v_mfma_f32_16x16x32_bf16 v[130:133], v[244:247], v[146:149], v[130:133]
	v_mfma_f32_16x16x32_bf16 v[134:137], v[244:247], v[150:153], v[134:137]
	v_mfma_f32_16x16x32_bf16 v[138:141], v[244:247], v[154:157], v[138:141]
	v_mfma_f32_16x16x32_bf16 v[142:145], v[244:247], v[158:161], v[142:145]
	ds_read2_b64 v[146:149], v217 offset0:56 offset1:60
	ds_read2_b64 v[150:153], v221 offset0:88 offset1:92
	ds_read2_b64 v[244:247], v222 offset0:120 offset1:124
	ds_read2_b64 v[248:251], v223 offset0:152 offset1:156
	v_cvt_pk_bf16_f32 v154, v102, v103
	v_cvt_pk_bf16_f32 v155, v104, v105
	v_cvt_pk_bf16_f32 v156, v110, v111
	v_cvt_pk_bf16_f32 v157, v112, v113
	s_waitcnt lgkmcnt(0)
	s_nop 0
	v_mfma_f32_16x16x32_bf16 v[158:161], v[154:157], v[228:231], v[166:169]
	v_mfma_f32_16x16x32_bf16 v[166:169], v[154:157], v[232:235], v[170:173]
	v_mfma_f32_16x16x32_bf16 v[170:173], v[154:157], v[236:239], v[174:177]
	v_mfma_f32_16x16x32_bf16 v[154:157], v[154:157], v[240:243], v[162:165]
	s_nop 2
	v_cvt_pk_bf16_f32 v162, v98, v99
	v_cvt_pk_bf16_f32 v163, v100, v101
	v_cvt_pk_bf16_f32 v164, v106, v107
	v_cvt_pk_bf16_f32 v165, v108, v109
	s_nop 1
	v_mfma_f32_16x16x32_bf16 v[174:177], v[162:165], v[228:231], v[130:133]
	v_mfma_f32_16x16x32_bf16 v[228:231], v[162:165], v[232:235], v[134:137]
	v_mfma_f32_16x16x32_bf16 v[232:235], v[162:165], v[236:239], v[138:141]
	v_mfma_f32_16x16x32_bf16 v[162:165], v[162:165], v[240:243], v[142:145]
	s_waitcnt vmcnt(0)
; __device__ __forceinline__ s16x4 ldtr(LAS const unsigned char* p) { return __builtin_bit_cast(s16x4, __builtin_amdgcn_ds_read_tr16_b64_v4i16((LAS s16x4*)p)); }
; #define LD_C2(buf, g) do { const int ks_ = (g) >> 3, t0_ = 2 * ((g) & 7); _Pragma("unroll") for (int t = 0; t < 2; ++t) { \
;                 fkt[buf][t][0] = ldtr(lds + SC_KI + (32 * ks_ + 8 * fq + q4) * SC_KS + (16 * (t0_ + t) + 4 * p4) * 2); \
;                 fkt[buf][t][1] = ldtr(lds + SC_KI + (32 * ks_ + 8 * fq + 4 + q4) * SC_KS + (16 * (t0_ + t) + 4 * p4) * 2); } } while (0)
; template <bool GLA>
; __device__ __forceinline__ void scan_item2(LAS unsigned char* lds, const bf16* Qd, const bf16* Kd, const bf16* V, bf16* O, const float* EG, int ldqk, int ldv, int b, int h, int dvs, float e_const, int tid) {
;     ...
; #pragma unroll
;             for (int ks = 0; ks < 2; ++ks)
; #pragma unroll
;                 for (int ct = 0; ct < 2; ++ct) { const s16x4 lo = ldtr(lds + SC_VI + (32 * ks + 8 * fq + q4) * SC_VS + (32 * w + 16 * ct + 4 * p4) * 2), hi = ldtr(lds + SC_VI + (32 * ks + 8 * fq + 4 + q4) * SC_VS + (32 * w + 16 * ct + 4 * p4) * 2);
;                     bv[ks][ct] = __builtin_shufflevector(lo, hi, 0, 1, 2, 3, 4, 5, 6, 7); }
; #pragma unroll
;             for (int g = 0; g < 16; ++g) {
;                 if (g + 2 < 16) LD_C2((g + 2) % 3, g + 2);
;                 __builtin_amdgcn_sched_barrier(0);
; #pragma unroll
;                 for (int t = 0; t < 2; ++t) { const bf16x8s ak = __builtin_shufflevector(fkt[g % 3][t][0], fkt[g % 3][t][1], 0, 1, 2, 3, 4, 5, 6, 7);
; #pragma unroll
;                     for (int ct = 0; ct < 2; ++ct) st[2 * (g & 7) + t][ct] = __builtin_amdgcn_mfma_f32_16x16x32_bf16(ak, bv[g >> 3][ct], st[2 * (g & 7) + t][ct], 0, 0, 0); }
	ds_read_b64_tr_b16 v[236:237], v194 offset:33792
	ds_read_b64_tr_b16 v[240:241], v194 offset:33824
	ds_read_b64_tr_b16 v[204:205], v194 offset:33856
	ds_read_b64_tr_b16 v[208:209], v194 offset:33888
	ds_read_b64_tr_b16 v[238:239], v194 offset:35968
	ds_read_b64_tr_b16 v[242:243], v194 offset:36000
	ds_read_b64_tr_b16 v[206:207], v194 offset:36032
	ds_read_b64_tr_b16 v[210:211], v194 offset:36064
	v_cvt_pk_bf16_f32 v142, v118, v119
	v_cvt_pk_bf16_f32 v143, v120, v121
	v_cvt_pk_bf16_f32 v144, v126, v127
	v_cvt_pk_bf16_f32 v145, v128, v129
	s_nop 1
	v_mfma_f32_16x16x32_bf16 v[134:137], v[142:145], v[150:153], v[166:169]
	s_nop 2
	v_cvt_pk_bf16_f32 v166, v114, v115
	v_cvt_pk_bf16_f32 v167, v116, v117
	v_cvt_pk_bf16_f32 v168, v122, v123
	v_cvt_pk_bf16_f32 v169, v124, v125
	v_mfma_f32_16x16x32_bf16 v[130:133], v[142:145], v[146:149], v[158:161]
	v_mfma_f32_16x16x32_bf16 v[138:141], v[142:145], v[244:247], v[170:173]
	v_mfma_f32_16x16x32_bf16 v[142:145], v[142:145], v[248:251], v[154:157]
	v_mfma_f32_16x16x32_bf16 v[158:161], v[166:169], v[146:149], v[174:177]
	v_mfma_f32_16x16x32_bf16 v[154:157], v[166:169], v[150:153], v[228:231]
	v_mfma_f32_16x16x32_bf16 v[150:153], v[166:169], v[244:247], v[232:235]
	v_mfma_f32_16x16x32_bf16 v[146:149], v[166:169], v[248:251], v[162:165]
	s_nop 2
	ds_read_b64_tr_b16 v[164:165], v1 offset:1152
	ds_read_b64_tr_b16 v[162:163], v1
	ds_read_b64_tr_b16 v[172:173], v1 offset:1184
	ds_read_b64_tr_b16 v[170:171], v1 offset:32
	ds_read_b64_tr_b16 v[166:167], v1 offset:9216
	ds_read_b64_tr_b16 v[168:169], v1 offset:10368
	ds_read_b64_tr_b16 v[176:177], v1 offset:10400
	ds_read_b64_tr_b16 v[174:175], v1 offset:9248
	ds_read_b64_tr_b16 v[230:231], v194 offset:36096
	ds_read_b64_tr_b16 v[228:229], v194 offset:33920
	ds_read_b64_tr_b16 v[234:235], v194 offset:36128
	ds_read_b64_tr_b16 v[232:233], v194 offset:33952
	s_waitcnt lgkmcnt(10)
	v_mfma_f32_16x16x32_bf16 v[6:9], v[236:239], v[162:165], v[6:9]
	s_waitcnt lgkmcnt(8)
	v_mfma_f32_16x16x32_bf16 v[2:5], v[236:239], v[170:173], v[2:5]
	v_mfma_f32_16x16x32_bf16 v[14:17], v[240:243], v[162:165], v[14:17]
	v_mfma_f32_16x16x32_bf16 v[10:13], v[240:243], v[170:173], v[10:13]
	ds_read_b64_tr_b16 v[238:239], v194 offset:36160
	ds_read_b64_tr_b16 v[236:237], v194 offset:33984
	ds_read_b64_tr_b16 v[242:243], v194 offset:36192
	ds_read_b64_tr_b16 v[240:241], v194 offset:34016
	v_mfma_f32_16x16x32_bf16 v[22:25], v[204:207], v[162:165], v[22:25]
	v_mfma_f32_16x16x32_bf16 v[18:21], v[204:207], v[170:173], v[18:21]
	v_mfma_f32_16x16x32_bf16 v[30:33], v[208:211], v[162:165], v[30:33]
	v_mfma_f32_16x16x32_bf16 v[26:29], v[208:211], v[170:173], v[26:29]
	ds_read_b64_tr_b16 v[206:207], v194 offset:36224
	ds_read_b64_tr_b16 v[204:205], v194 offset:34048
	ds_read_b64_tr_b16 v[210:211], v194 offset:36256
	ds_read_b64_tr_b16 v[208:209], v194 offset:34080
	s_waitcnt lgkmcnt(10)
	v_mfma_f32_16x16x32_bf16 v[38:41], v[228:231], v[162:165], v[38:41]
	v_mfma_f32_16x16x32_bf16 v[34:37], v[228:231], v[170:173], v[34:37]
	s_waitcnt lgkmcnt(8)
	v_mfma_f32_16x16x32_bf16 v[46:49], v[232:235], v[162:165], v[46:49]
	v_mfma_f32_16x16x32_bf16 v[42:45], v[232:235], v[170:173], v[42:45]
	ds_read_b64_tr_b16 v[230:231], v194 offset:36288
	ds_read_b64_tr_b16 v[228:229], v194 offset:34112
	ds_read_b64_tr_b16 v[234:235], v194 offset:36320
	ds_read_b64_tr_b16 v[232:233], v194 offset:34144
	s_waitcnt lgkmcnt(10)
	v_mfma_f32_16x16x32_bf16 v[54:57], v[236:239], v[162:165], v[54:57]
	v_mfma_f32_16x16x32_bf16 v[50:53], v[236:239], v[170:173], v[50:53]
	s_waitcnt lgkmcnt(8)
	v_mfma_f32_16x16x32_bf16 v[62:65], v[240:243], v[162:165], v[62:65]
	v_mfma_f32_16x16x32_bf16 v[58:61], v[240:243], v[170:173], v[58:61]
	ds_read_b64_tr_b16 v[238:239], v194 offset:36352
	ds_read_b64_tr_b16 v[236:237], v194 offset:34176
	ds_read_b64_tr_b16 v[242:243], v194 offset:36384
	ds_read_b64_tr_b16 v[240:241], v194 offset:34208
	s_waitcnt lgkmcnt(10)
	v_mfma_f32_16x16x32_bf16 v[70:73], v[204:207], v[162:165], v[70:73]
	v_mfma_f32_16x16x32_bf16 v[66:69], v[204:207], v[170:173], v[66:69]
	s_waitcnt lgkmcnt(8)
	v_mfma_f32_16x16x32_bf16 v[78:81], v[208:211], v[162:165], v[78:81]
	v_mfma_f32_16x16x32_bf16 v[74:77], v[208:211], v[170:173], v[74:77]
	ds_read_b64_tr_b16 v[206:207], v194 offset:36416
	ds_read_b64_tr_b16 v[204:205], v194 offset:34240
	ds_read_b64_tr_b16 v[210:211], v194 offset:36448
	ds_read_b64_tr_b16 v[208:209], v194 offset:34272
	s_waitcnt lgkmcnt(10)
	v_mfma_f32_16x16x32_bf16 v[86:89], v[228:231], v[162:165], v[86:89]
	v_mfma_f32_16x16x32_bf16 v[82:85], v[228:231], v[170:173], v[82:85]
	s_waitcnt lgkmcnt(8)
	v_mfma_f32_16x16x32_bf16 v[94:97], v[232:235], v[162:165], v[94:97]
	v_mfma_f32_16x16x32_bf16 v[90:93], v[232:235], v[170:173], v[90:93]
	ds_read_b64_tr_b16 v[230:231], v194 offset:53376
	ds_read_b64_tr_b16 v[228:229], v194 offset:51200
	ds_read_b64_tr_b16 v[234:235], v194 offset:53408
	ds_read_b64_tr_b16 v[232:233], v194 offset:51232
	s_waitcnt lgkmcnt(10)
	v_mfma_f32_16x16x32_bf16 v[102:105], v[236:239], v[162:165], v[102:105]
	v_mfma_f32_16x16x32_bf16 v[98:101], v[236:239], v[170:173], v[98:101]
	s_waitcnt lgkmcnt(8)
	v_mfma_f32_16x16x32_bf16 v[110:113], v[240:243], v[162:165], v[110:113]
	v_mfma_f32_16x16x32_bf16 v[106:109], v[240:243], v[170:173], v[106:109]
	ds_read_b64_tr_b16 v[238:239], v194 offset:53440
	ds_read_b64_tr_b16 v[236:237], v194 offset:51264
	ds_read_b64_tr_b16 v[242:243], v194 offset:53472
	ds_read_b64_tr_b16 v[240:241], v194 offset:51296
	s_waitcnt lgkmcnt(10)
	v_mfma_f32_16x16x32_bf16 v[118:121], v[204:207], v[162:165], v[118:121]
	v_mfma_f32_16x16x32_bf16 v[114:117], v[204:207], v[170:173], v[114:117]
	s_waitcnt lgkmcnt(8)
; #define LAS __attribute__((address_space(3)))
; #define LD_C2(buf, g) do { const int ks_ = (g) >> 3, t0_ = 2 * ((g) & 7); _Pragma("unroll") for (int t = 0; t < 2; ++t) { \
;                 fkt[buf][t][0] = ldtr(lds + SC_KI + (32 * ks_ + 8 * fq + q4) * SC_KS + (16 * (t0_ + t) + 4 * p4) * 2); \
;                 fkt[buf][t][1] = ldtr(lds + SC_KI + (32 * ks_ + 8 * fq + 4 + q4) * SC_KS + (16 * (t0_ + t) + 4 * p4) * 2); } } while (0)
; template <bool GLA>
; __device__ __forceinline__ void scan_item2(LAS unsigned char* lds, const bf16* Qd, const bf16* Kd, const bf16* V, bf16* O, const float* EG, int ldqk, int ldv, int b, int h, int dvs, float e_const, int tid) {
;     ...
; #pragma unroll
;             for (int g = 0; g < 16; ++g) {
;                 if (g + 2 < 16) LD_C2((g + 2) % 3, g + 2);
;                 __builtin_amdgcn_sched_barrier(0);
; #pragma unroll
;                 for (int t = 0; t < 2; ++t) { const bf16x8s ak = __builtin_shufflevector(fkt[g % 3][t][0], fkt[g % 3][t][1], 0, 1, 2, 3, 4, 5, 6, 7);
; #pragma unroll
;                     for (int ct = 0; ct < 2; ++ct) st[2 * (g & 7) + t][ct] = __builtin_amdgcn_mfma_f32_16x16x32_bf16(ak, bv[g >> 3][ct], st[2 * (g & 7) + t][ct], 0, 0, 0); }
;                 __builtin_amdgcn_sched_barrier(0);
;             }
;     ...
; #pragma unroll
;             for (int t = 0; t < 16; ++t) { if (GLA) { const f32x4 e4 = *(const LAS f32x4*)(lds + SC_EI + (16 * t + 4 * fq) * 4); st[t][0] = st[t][0] * e4; st[t][1] = st[t][1] * e4; } else { st[t][0] = st[t][0] * e_const; st[t][1] = st[t][1] * e_const; } }
	v_mfma_f32_16x16x32_bf16 v[126:129], v[208:211], v[162:165], v[126:129]
	v_mfma_f32_16x16x32_bf16 v[122:125], v[208:211], v[170:173], v[122:125]
	ds_read_b64_tr_b16 v[206:207], v194 offset:53504
	ds_read_b64_tr_b16 v[204:205], v194 offset:51328
	ds_read_b64_tr_b16 v[210:211], v194 offset:53536
	ds_read_b64_tr_b16 v[208:209], v194 offset:51360
	s_waitcnt lgkmcnt(10)
	v_mfma_f32_16x16x32_bf16 v[6:9], v[228:231], v[166:169], v[6:9]
	v_mfma_f32_16x16x32_bf16 v[2:5], v[228:231], v[174:177], v[2:5]
	s_waitcnt lgkmcnt(8)
	v_mfma_f32_16x16x32_bf16 v[14:17], v[232:235], v[166:169], v[14:17]
	v_mfma_f32_16x16x32_bf16 v[10:13], v[232:235], v[174:177], v[10:13]
	ds_read_b64_tr_b16 v[230:231], v194 offset:53568
	ds_read_b64_tr_b16 v[228:229], v194 offset:51392
	ds_read_b64_tr_b16 v[234:235], v194 offset:53600
	ds_read_b64_tr_b16 v[232:233], v194 offset:51424
	s_waitcnt lgkmcnt(10)
	v_mfma_f32_16x16x32_bf16 v[22:25], v[236:239], v[166:169], v[22:25]
	v_mfma_f32_16x16x32_bf16 v[18:21], v[236:239], v[174:177], v[18:21]
	s_waitcnt lgkmcnt(8)
	v_mfma_f32_16x16x32_bf16 v[30:33], v[240:243], v[166:169], v[30:33]
	v_mfma_f32_16x16x32_bf16 v[26:29], v[240:243], v[174:177], v[26:29]
	ds_read_b64_tr_b16 v[238:239], v194 offset:53632
	ds_read_b64_tr_b16 v[236:237], v194 offset:51456
	ds_read_b64_tr_b16 v[242:243], v194 offset:53664
	ds_read_b64_tr_b16 v[240:241], v194 offset:51488
	s_waitcnt lgkmcnt(10)
	v_mfma_f32_16x16x32_bf16 v[38:41], v[204:207], v[166:169], v[38:41]
	v_mfma_f32_16x16x32_bf16 v[34:37], v[204:207], v[174:177], v[34:37]
	s_waitcnt lgkmcnt(8)
	v_mfma_f32_16x16x32_bf16 v[46:49], v[208:211], v[166:169], v[46:49]
	v_mfma_f32_16x16x32_bf16 v[42:45], v[208:211], v[174:177], v[42:45]
	ds_read_b64_tr_b16 v[206:207], v194 offset:53696
	ds_read_b64_tr_b16 v[204:205], v194 offset:51520
	ds_read_b64_tr_b16 v[210:211], v194 offset:53728
	ds_read_b64_tr_b16 v[208:209], v194 offset:51552
	s_waitcnt lgkmcnt(10)
	v_mfma_f32_16x16x32_bf16 v[54:57], v[228:231], v[166:169], v[54:57]
	v_mfma_f32_16x16x32_bf16 v[50:53], v[228:231], v[174:177], v[50:53]
	s_waitcnt lgkmcnt(8)
	v_mfma_f32_16x16x32_bf16 v[62:65], v[232:235], v[166:169], v[62:65]
	v_mfma_f32_16x16x32_bf16 v[58:61], v[232:235], v[174:177], v[58:61]
	ds_read_b64_tr_b16 v[230:231], v194 offset:53760
	ds_read_b64_tr_b16 v[228:229], v194 offset:51584
	ds_read_b64_tr_b16 v[234:235], v194 offset:53792
	ds_read_b64_tr_b16 v[232:233], v194 offset:51616
	s_waitcnt lgkmcnt(10)
	v_mfma_f32_16x16x32_bf16 v[70:73], v[236:239], v[166:169], v[70:73]
	v_mfma_f32_16x16x32_bf16 v[66:69], v[236:239], v[174:177], v[66:69]
	s_waitcnt lgkmcnt(8)
	v_mfma_f32_16x16x32_bf16 v[78:81], v[240:243], v[166:169], v[78:81]
	v_mfma_f32_16x16x32_bf16 v[74:77], v[240:243], v[174:177], v[74:77]
	ds_read_b64_tr_b16 v[238:239], v194 offset:53824
	ds_read_b64_tr_b16 v[236:237], v194 offset:51648
	ds_read_b64_tr_b16 v[242:243], v194 offset:53856
	ds_read_b64_tr_b16 v[240:241], v194 offset:51680
	s_waitcnt lgkmcnt(10)
	v_mfma_f32_16x16x32_bf16 v[86:89], v[204:207], v[166:169], v[86:89]
	v_mfma_f32_16x16x32_bf16 v[82:85], v[204:207], v[174:177], v[82:85]
	s_waitcnt lgkmcnt(8)
	v_mfma_f32_16x16x32_bf16 v[94:97], v[208:211], v[166:169], v[94:97]
	v_mfma_f32_16x16x32_bf16 v[90:93], v[208:211], v[174:177], v[90:93]
	s_waitcnt lgkmcnt(6)
	v_mfma_f32_16x16x32_bf16 v[102:105], v[228:231], v[166:169], v[102:105]
	v_mfma_f32_16x16x32_bf16 v[98:101], v[228:231], v[174:177], v[98:101]
	s_waitcnt lgkmcnt(4)
	v_mfma_f32_16x16x32_bf16 v[110:113], v[232:235], v[166:169], v[110:113]
	v_mfma_f32_16x16x32_bf16 v[106:109], v[232:235], v[174:177], v[106:109]
	s_waitcnt lgkmcnt(2)
	v_mfma_f32_16x16x32_bf16 v[118:121], v[236:239], v[166:169], v[118:121]
	v_mfma_f32_16x16x32_bf16 v[114:117], v[236:239], v[174:177], v[114:117]
	s_waitcnt lgkmcnt(0)
	v_mfma_f32_16x16x32_bf16 v[126:129], v[240:243], v[166:169], v[126:129]
	v_mfma_f32_16x16x32_bf16 v[122:125], v[240:243], v[174:177], v[122:125]
	ds_read_b128 v[204:207], v218
	s_waitcnt lgkmcnt(0)
	v_pk_mul_f32 v[8:9], v[8:9], v[206:207]
	v_pk_mul_f32 v[6:7], v[6:7], v[204:205]
	v_pk_mul_f32 v[4:5], v[4:5], v[206:207]
	v_pk_mul_f32 v[2:3], v[2:3], v[204:205]
	ds_read_b128 v[204:207], v218 offset:64
	s_waitcnt lgkmcnt(0)
	v_pk_mul_f32 v[16:17], v[16:17], v[206:207]
	v_pk_mul_f32 v[14:15], v[14:15], v[204:205]
	v_pk_mul_f32 v[12:13], v[12:13], v[206:207]
	v_pk_mul_f32 v[10:11], v[10:11], v[204:205]
	ds_read_b128 v[204:207], v218 offset:128
	s_waitcnt lgkmcnt(0)
	v_pk_mul_f32 v[24:25], v[24:25], v[206:207]
	v_pk_mul_f32 v[22:23], v[22:23], v[204:205]
	v_pk_mul_f32 v[20:21], v[20:21], v[206:207]
	v_pk_mul_f32 v[18:19], v[18:19], v[204:205]
	ds_read_b128 v[204:207], v218 offset:192
	s_waitcnt lgkmcnt(0)
	v_pk_mul_f32 v[32:33], v[32:33], v[206:207]
	v_pk_mul_f32 v[30:31], v[30:31], v[204:205]
	v_pk_mul_f32 v[28:29], v[28:29], v[206:207]
	v_pk_mul_f32 v[26:27], v[26:27], v[204:205]
	ds_read_b128 v[204:207], v218 offset:256
	s_waitcnt lgkmcnt(0)
	v_pk_mul_f32 v[40:41], v[40:41], v[206:207]
	v_pk_mul_f32 v[38:39], v[38:39], v[204:205]
	v_pk_mul_f32 v[36:37], v[36:37], v[206:207]
	v_pk_mul_f32 v[34:35], v[34:35], v[204:205]
	ds_read_b128 v[204:207], v218 offset:320
	s_waitcnt lgkmcnt(0)
	v_pk_mul_f32 v[48:49], v[48:49], v[206:207]
	v_pk_mul_f32 v[46:47], v[46:47], v[204:205]
	v_pk_mul_f32 v[44:45], v[44:45], v[206:207]
	v_pk_mul_f32 v[42:43], v[42:43], v[204:205]
	ds_read_b128 v[204:207], v218 offset:384
	s_waitcnt lgkmcnt(0)
	v_pk_mul_f32 v[56:57], v[56:57], v[206:207]
	v_pk_mul_f32 v[54:55], v[54:55], v[204:205]
	v_pk_mul_f32 v[52:53], v[52:53], v[206:207]
	v_pk_mul_f32 v[50:51], v[50:51], v[204:205]
	ds_read_b128 v[204:207], v218 offset:448
	s_waitcnt lgkmcnt(0)
; #define LAS __attribute__((address_space(3)))
; __device__ __forceinline__ unsigned cvt2(float a, float b) { f32x2s v = {a, b}; bf16x2_t r = __builtin_convertvector(v, bf16x2_t); return __builtin_bit_cast(unsigned, r); }
; #define SC_BAR() do { asm volatile("s_waitcnt lgkmcnt(0)" ::: "memory"); __builtin_amdgcn_s_barrier(); asm volatile("" ::: "memory"); } while (0)
; template <bool GLA>
; __device__ __forceinline__ void scan_item2(LAS unsigned char* lds, const bf16* Qd, const bf16* Kd, const bf16* V, bf16* O, const float* EG, int ldqk, int ldv, int b, int h, int dvs, float e_const, int tid) {
;     ...
;             for (int t = 0; t < 16; ++t) { if (GLA) { const f32x4 e4 = *(const LAS f32x4*)(lds + SC_EI + (16 * t + 4 * fq) * 4); st[t][0] = st[t][0] * e4; st[t][1] = st[t][1] * e4; } else { st[t][0] = st[t][0] * e_const; st[t][1] = st[t][1] * e_const; } }
;             SC_BAR();
; #pragma unroll
;             for (int ks = 0; ks < 2; ++ks) { bf16x8s ap[4];
; #pragma unroll
;                 for (int ti = 0; ti < 4; ++ti) ap[ti] = *(const LAS bf16x8s*)(lds + SC_PI + (16 * ti + fr) * SC_PS + (32 * ks + 8 * fq) * 2);
; #pragma unroll
;                 for (int ti = 0; ti < 4; ++ti)
; #pragma unroll
;                     for (int ct = 0; ct < 2; ++ct) oa[ti][ct] = __builtin_amdgcn_mfma_f32_16x16x32_bf16(bv[ks][ct], ap[ti], oa[ti][ct], 0, 0, 0); }
; #pragma unroll
;             for (int ti = 0; ti < 4; ++ti)
; #pragma unroll
;                 for (int ct = 0; ct < 2; ++ct) { v2u ow; ow.x = cvt2(oa[ti][ct][0], oa[ti][ct][1]); ow.y = cvt2(oa[ti][ct][2], oa[ti][ct][3]);
;                     *(v2u*)((char*)(obase + ((size_t)c * 64 + 16 * ti) * ldv + 16 * ct) + ooff) = ow; }
;         }
;         SC_BAR();
	v_pk_mul_f32 v[64:65], v[64:65], v[206:207]
	v_pk_mul_f32 v[62:63], v[62:63], v[204:205]
	v_pk_mul_f32 v[60:61], v[60:61], v[206:207]
	v_pk_mul_f32 v[58:59], v[58:59], v[204:205]
	ds_read_b128 v[204:207], v218 offset:512
	s_waitcnt lgkmcnt(0)
	v_pk_mul_f32 v[72:73], v[72:73], v[206:207]
	v_pk_mul_f32 v[70:71], v[70:71], v[204:205]
	v_pk_mul_f32 v[68:69], v[68:69], v[206:207]
	v_pk_mul_f32 v[66:67], v[66:67], v[204:205]
	ds_read_b128 v[204:207], v218 offset:576
	s_waitcnt lgkmcnt(0)
	v_pk_mul_f32 v[80:81], v[80:81], v[206:207]
	v_pk_mul_f32 v[78:79], v[78:79], v[204:205]
	v_pk_mul_f32 v[76:77], v[76:77], v[206:207]
	v_pk_mul_f32 v[74:75], v[74:75], v[204:205]
	ds_read_b128 v[204:207], v218 offset:640
	s_waitcnt lgkmcnt(0)
	v_pk_mul_f32 v[88:89], v[88:89], v[206:207]
	v_pk_mul_f32 v[86:87], v[86:87], v[204:205]
	v_pk_mul_f32 v[84:85], v[84:85], v[206:207]
	v_pk_mul_f32 v[82:83], v[82:83], v[204:205]
	ds_read_b128 v[204:207], v218 offset:704
	s_waitcnt lgkmcnt(0)
	v_pk_mul_f32 v[96:97], v[96:97], v[206:207]
	v_pk_mul_f32 v[94:95], v[94:95], v[204:205]
	v_pk_mul_f32 v[92:93], v[92:93], v[206:207]
	v_pk_mul_f32 v[90:91], v[90:91], v[204:205]
	ds_read_b128 v[204:207], v218 offset:768
	s_waitcnt lgkmcnt(0)
	v_pk_mul_f32 v[104:105], v[104:105], v[206:207]
	v_pk_mul_f32 v[102:103], v[102:103], v[204:205]
	v_pk_mul_f32 v[100:101], v[100:101], v[206:207]
	v_pk_mul_f32 v[98:99], v[98:99], v[204:205]
	ds_read_b128 v[204:207], v218 offset:832
	s_waitcnt lgkmcnt(0)
	v_pk_mul_f32 v[112:113], v[112:113], v[206:207]
	v_pk_mul_f32 v[110:111], v[110:111], v[204:205]
	v_pk_mul_f32 v[108:109], v[108:109], v[206:207]
	v_pk_mul_f32 v[106:107], v[106:107], v[204:205]
	ds_read_b128 v[204:207], v218 offset:896
	s_waitcnt lgkmcnt(0)
	v_pk_mul_f32 v[120:121], v[120:121], v[206:207]
	v_pk_mul_f32 v[118:119], v[118:119], v[204:205]
	v_pk_mul_f32 v[116:117], v[116:117], v[206:207]
	v_pk_mul_f32 v[114:115], v[114:115], v[204:205]
	ds_read_b128 v[204:207], v218 offset:960
	s_waitcnt lgkmcnt(0)
	s_barrier
	s_waitcnt lgkmcnt(0)
	v_pk_mul_f32 v[128:129], v[128:129], v[206:207]
	v_pk_mul_f32 v[126:127], v[126:127], v[204:205]
	v_pk_mul_f32 v[124:125], v[124:125], v[206:207]
	v_pk_mul_f32 v[122:123], v[122:123], v[204:205]
	ds_read_b128 v[204:207], v219
	ds_read_b128 v[208:211], v219 offset:2560
	ds_read_b128 v[228:231], v219 offset:5120
	ds_read_b128 v[232:235], v219 offset:7680
	s_waitcnt lgkmcnt(3)
	v_mfma_f32_16x16x32_bf16 v[130:133], v[162:165], v[204:207], v[130:133]
	v_mfma_f32_16x16x32_bf16 v[158:161], v[170:173], v[204:207], v[158:161]
	s_waitcnt lgkmcnt(2)
	v_mfma_f32_16x16x32_bf16 v[134:137], v[162:165], v[208:211], v[134:137]
	v_mfma_f32_16x16x32_bf16 v[154:157], v[170:173], v[208:211], v[154:157]
	s_waitcnt lgkmcnt(1)
	v_mfma_f32_16x16x32_bf16 v[138:141], v[162:165], v[228:231], v[138:141]
	v_mfma_f32_16x16x32_bf16 v[150:153], v[170:173], v[228:231], v[150:153]
	s_waitcnt lgkmcnt(0)
	v_mfma_f32_16x16x32_bf16 v[142:145], v[162:165], v[232:235], v[142:145]
	v_mfma_f32_16x16x32_bf16 v[146:149], v[170:173], v[232:235], v[146:149]
	ds_read_b128 v[162:165], v219 offset:64
	ds_read_b128 v[170:173], v219 offset:2624
	ds_read_b128 v[204:207], v219 offset:5184
	ds_read_b128 v[208:211], v219 offset:7744
	s_waitcnt lgkmcnt(3)
	v_mfma_f32_16x16x32_bf16 v[130:133], v[166:169], v[162:165], v[130:133]
	v_mfma_f32_16x16x32_bf16 v[158:161], v[174:177], v[162:165], v[158:161]
	v_lshl_add_u64 v[162:163], v[190:191], 0, s[10:11]
	s_nop 5
	v_cvt_pk_bf16_f32 v130, v130, v131
	v_cvt_pk_bf16_f32 v131, v132, v133
	s_waitcnt lgkmcnt(2)
	v_mfma_f32_16x16x32_bf16 v[134:137], v[166:169], v[170:173], v[134:137]
	v_add_co_u32_e32 v132, vcc, s45, v162
	s_add_u32 s10, s10, 0x40000
	v_mfma_f32_16x16x32_bf16 v[154:157], v[174:177], v[170:173], v[154:157]
	v_addc_co_u32_e32 v133, vcc, 0, v163, vcc
	global_store_dwordx2 v[132:133], v[130:131], off
	v_cvt_pk_bf16_f32 v130, v158, v159
	v_cvt_pk_bf16_f32 v131, v160, v161
	s_waitcnt lgkmcnt(1)
	v_mfma_f32_16x16x32_bf16 v[138:141], v[166:169], v[204:207], v[138:141]
	global_store_dwordx2 v[132:133], v[130:131], off offset:32
	v_add_co_u32_e32 v132, vcc, s46, v162
	v_mfma_f32_16x16x32_bf16 v[150:153], v[174:177], v[204:207], v[150:153]
	v_cvt_pk_bf16_f32 v130, v134, v135
	v_cvt_pk_bf16_f32 v131, v136, v137
	v_addc_co_u32_e32 v133, vcc, 0, v163, vcc
	global_store_dwordx2 v[132:133], v[130:131], off
	v_cvt_pk_bf16_f32 v130, v154, v155
	v_cvt_pk_bf16_f32 v131, v156, v157
	s_waitcnt lgkmcnt(0)
	v_mfma_f32_16x16x32_bf16 v[142:145], v[166:169], v[208:211], v[142:145]
	global_store_dwordx2 v[132:133], v[130:131], off offset:32
	v_add_co_u32_e32 v132, vcc, s47, v162
	v_mfma_f32_16x16x32_bf16 v[146:149], v[174:177], v[208:211], v[146:149]
	v_cvt_pk_bf16_f32 v130, v138, v139
	v_cvt_pk_bf16_f32 v131, v140, v141
	v_addc_co_u32_e32 v133, vcc, 0, v163, vcc
	global_store_dwordx2 v[132:133], v[130:131], off
	v_cvt_pk_bf16_f32 v130, v150, v151
	v_cvt_pk_bf16_f32 v131, v152, v153
	global_store_dwordx2 v[132:133], v[130:131], off offset:32
	v_add_co_u32_e32 v132, vcc, s52, v162
	v_cvt_pk_bf16_f32 v130, v142, v143
	v_cvt_pk_bf16_f32 v131, v144, v145
	v_addc_co_u32_e32 v133, vcc, 0, v163, vcc
	s_addc_u32 s11, s11, 0
	global_store_dwordx2 v[132:133], v[130:131], off
	v_cvt_pk_bf16_f32 v130, v146, v147
	v_cvt_pk_bf16_f32 v131, v148, v149
	s_cmp_eq_u32 s10, 0x800000
	global_store_dwordx2 v[132:133], v[130:131], off offset:32
	s_cbranch_scc0 .LBB0_1911
	s_setprio 0
	s_waitcnt lgkmcnt(0)
	s_barrier
	s_branch .LBB0_1907
